# fusedln
# speedup vs baseline: 1.0343x; 1.0077x over previous
; __device__ __forceinline__ void convert_phase(const Params& p, char* shm) {
;     ...
;   {
;     float4* z4 = (float4*)(p.ws + OFF_ST1);
;     int n4 = M_TOK * 2 * 2 / 4;
;     for (int i = blockIdx.x * 512 + threadIdx.x; i < n4; i += gridDim.x * 512) z4[i] = make_float4(0.f, 0.f, 0.f, 0.f);
;   }
; template <int EPI>
; __device__ __forceinline__ void gemm_phase(const u16* __restrict__ A, const u16* __restrict__ Bt, const int K,
;                                            const int nN, char* shm, const EpiArgs& ea) {
;     ...
;   const int nM = M_TOK / BM;
;   const int nwg = nM * nN;
;   const int G = gridDim.x, bid = blockIdx.x;
;   const bool remap = ((G & 7) == 0) && (nwg % G == 0);
;   const int nig = 8 * nN;
;   const int nt = K / BK;
;   const int Lofs = remap ? (bid & 7) * (G >> 3) + (bid >> 3) : bid;
;   int brow = 0, bcol = 0, pn = 0;
;   if (Lofs < nwg) {
;     TILE_RC(Lofs, brow, bcol, pn);
;     STAGE7(brow, bcol);
;   }
.LBB0_554:
	s_add_u32 s100, s90, 0x1da20000
	s_addc_u32 s101, s91, 0
	s_lshl_b32 s98, s96, 9
	v_lshlrev_b32_e32 v0, 4, v174
	v_add_u32_e32 v0, s98, v0
	v_mov_b32_e32 v4, 0
	v_mov_b32_e32 v5, 0
	v_mov_b32_e32 v6, 0
	v_mov_b32_e32 v7, 0
	v_cmp_gt_u32_e32 vcc, 32, v174
	s_and_saveexec_b64 s[98:99], vcc
	global_store_dwordx4 v0, v[4:7], s[100:101]
	s_or_b64 exec, exec, s[98:99]
	s_and_b32 s0, s94, 7
	v_readfirstlane_b32 s20, v174
	s_cmp_lg_u32 s0, 0
	s_mov_b32 s25, s96
	s_cbranch_scc1 .LBB0_557
	s_abs_i32 s0, s94
	s_waitcnt vmcnt(2)
	v_cvt_f32_u32_e32 v0, s0
	s_sub_i32 s1, 0, s0
	s_mov_b32 s25, s96
	v_rcp_iflag_f32_e32 v0, v0
	s_nop 0
	v_mul_f32_e32 v0, 0x4f7ffffe, v0
	v_cvt_u32_f32_e32 v0, v0
	s_nop 0
	v_readfirstlane_b32 s2, v0
	s_mul_i32 s1, s1, s2
	s_mul_hi_u32 s1, s2, s1
	s_add_i32 s2, s2, s1
	s_mul_hi_u32 s1, s2, 0xb00
	s_mul_i32 s1, s1, s0
	s_sub_i32 s1, 0xb00, s1
	s_sub_i32 s2, s1, s0
	s_cmp_ge_u32 s1, s0
	s_cselect_b32 s1, s2, s1
	s_sub_i32 s2, s1, s0
	s_cmp_ge_u32 s1, s0
	s_cselect_b32 s0, s2, s1
	s_cmp_lg_u32 s0, 0
	s_cbranch_scc1 .LBB0_557
	s_and_b32 s0, s96, 7
	s_ashr_i32 s1, s94, 3
	s_mul_i32 s0, s1, s0
	s_ashr_i32 s1, s96, 3
	s_add_i32 s25, s0, s1

; template <int EPI>
; __device__ __forceinline__ void gemm_phase(const u16* __restrict__ A, const u16* __restrict__ Bt, const int K,
;                                            const int nN, char* shm, const EpiArgs& ea) {
;     ...
;               float mu = 0.f, rstd = 1.f;
;               if (EPI != EPI_FFN1) row_stats(ea.st_in, row, mu, rstd);
;               float rs = 0.f, rq = 0.f;
; #pragma unroll
;               for (int bj = 0; bj < 2; ++bj) {
;                 uint2 pk[2];
; #pragma unroll
;                 for (int n = 0; n < 2; ++n) {
;                   const int col = cb + bj * 128 + n * 16;
;                   f32x4 c = acc[ai][bj][m][n];
;                   float h[4];
;                   if (EPI == EPI_FFN1) {
;                     float4 rv = *(const float4*)(ea.res + (size_t)row * DM + col);
;                     h[0] = rv.x; h[1] = rv.y; h[2] = rv.z; h[3] = rv.w;
;                   } else {
;                     uint2 yv = *(const uint2*)((const char*)ea.yb + tl_off(row, col, DM >> 6));
;                     float4 gv = *(const float4*)(ea.lng + col);
;                     float4 bv = *(const float4*)(ea.lnb + col);
;                     h[0] = (bf_lo(yv.x) - mu) * rstd * gv.x + bv.x; h[1] = (bf_hi(yv.x) - mu) * rstd * gv.y + bv.y;
;                     h[2] = (bf_lo(yv.y) - mu) * rstd * gv.z + bv.z; h[3] = (bf_hi(yv.y) - mu) * rstd * gv.w + bv.w;
;                   }
;                   float y[4];
;                   if (EPI == EPI_OUT) {
;                     float4 bo = *(const float4*)(ea.bias + col);
;                     y[0] = ALPHA * h[0] + c[0] + bo.x; y[1] = ALPHA * h[1] + c[1] + bo.y;
;                     y[2] = ALPHA * h[2] + c[2] + bo.z; y[3] = ALPHA * h[3] + c[3] + bo.w;
;                   } else {
; #pragma unroll
;                     for (int j = 0; j < 4; ++j) y[j] = ALPHA * h[j] + 0.5f * c[j];
;                   }
;                   if (EPI == EPI_FFN2) {
;                     *(float4*)(ea.outf + (size_t)row * DM + col) = make_float4(y[0], y[1], y[2], y[3]);
;                   } else {
;                     pk[n] = make_uint2(pack2(y[0], y[1]), pack2(y[2], y[3]));
;                     float q0 = bf_lo(pk[n].x), q1 = bf_hi(pk[n].x), q2 = bf_lo(pk[n].y), q3 = bf_hi(pk[n].y);
;                     rs += (q0 + q1) + (q2 + q3);
;                     rq += (q0 * q0 + q1 * q1) + (q2 * q2 + q3 * q3);
;                   }
.LBB0_625:
	s_lshr_b32 s98, s33, 7
	s_mul_i32 s98, s98, 0x84000
	s_lshr_b32 s99, s47, 6
	s_lshl_b32 s99, s99, 14
	s_add_i32 s98, s98, s99
	s_lshr_b32 s99, s33, 8
	s_lshl_b32 s99, s99, 5
	s_add_i32 s100, s99, 0x1da81c00
	v_add_u32_e32 v170, s33, v139
	v_add_u32_e32 v171, s47, v140
	v_lshlrev_b32_e32 v172, 3, v170
	v_add_u32_e32 v252, 0x1da20000, v172
	v_lshlrev_b32_e32 v173, 2, v171
	global_load_dwordx2 v[150:151], v172, s[8:9]
	global_load_dwordx2 v[152:153], v172, s[8:9] offset:128
	global_load_dwordx2 v[154:155], v172, s[8:9] offset:256
	global_load_dwordx2 v[156:157], v172, s[8:9] offset:384
	global_load_dwordx2 v[158:159], v172, s[8:9] offset:1024
	global_load_dwordx2 v[160:161], v172, s[8:9] offset:1152
	global_load_dwordx2 v[162:163], v172, s[8:9] offset:1280
	global_load_dwordx2 v[164:165], v172, s[8:9] offset:1408
	global_load_dwordx4 v[176:179], v173, s[22:23]
	global_load_dwordx4 v[192:195], v173, s[76:77]
	global_load_dwordx4 v[180:183], v173, s[22:23] offset:64
	global_load_dwordx4 v[196:199], v173, s[76:77] offset:64
	global_load_dwordx4 v[184:187], v173, s[22:23] offset:512
	global_load_dwordx4 v[200:203], v173, s[76:77] offset:512
	global_load_dwordx4 v[188:191], v173, s[22:23] offset:576
	global_load_dwordx4 v[204:207], v173, s[76:77] offset:576
	v_and_b32_e32 v132, 15, v174
	v_lshlrev_b32_e32 v130, 6, v132
	v_and_b32_e32 v132, 48, v174
	v_lshrrev_b32_e32 v132, 1, v132
	v_or_b32_e32 v130, v130, v132
	v_and_b32_e32 v132, 64, v174
	v_lshl_or_b32 v130, v132, 4, v130
	v_and_b32_e32 v132, 0x80, v174
	v_lshl_or_b32 v130, v132, 7, v130
	v_and_b32_e32 v132, 0x100, v174
	v_lshl_or_b32 v130, v132, 5, v130
	v_add_u32_e32 v130, s98, v130
	v_and_b32_e32 v175, 8, v174
	v_lshlrev_b32_e32 v175, 2, v175
	v_sub_u32_e32 v131, v130, v175
	v_add_u32_e32 v131, 32, v131
	v_add_u32_e32 v130, v130, v175
	v_lshl_add_u32 v128, v170, 13, v173
	global_load_dwordx2 v[208:209], v130, s[10:11]
	global_load_dwordx2 v[210:211], v131, s[10:11]
	v_add_u32_e32 v132, 0x8000, v130
	global_load_dwordx2 v[212:213], v132, s[10:11]
	v_add_u32_e32 v149, 0x8000, v131
	global_load_dwordx2 v[214:215], v149, s[10:11]
	v_add_u32_e32 v132, 0x800, v130
	global_load_dwordx2 v[216:217], v132, s[10:11]
	v_add_u32_e32 v149, 0x800, v131
	global_load_dwordx2 v[218:219], v149, s[10:11]
	v_add_u32_e32 v132, 0x8800, v130
	global_load_dwordx2 v[220:221], v132, s[10:11]
	v_add_u32_e32 v149, 0x8800, v131
	global_load_dwordx2 v[222:223], v149, s[10:11]
	v_add_u32_e32 v132, 0x1000, v130
	global_load_dwordx2 v[224:225], v132, s[10:11]
	v_add_u32_e32 v149, 0x1000, v131
	global_load_dwordx2 v[226:227], v149, s[10:11]
	v_add_u32_e32 v132, 0x9000, v130
	global_load_dwordx2 v[228:229], v132, s[10:11]
	v_add_u32_e32 v149, 0x9000, v131
	global_load_dwordx2 v[230:231], v149, s[10:11]
	v_add_u32_e32 v132, 0x1800, v130
	global_load_dwordx2 v[232:233], v132, s[10:11]
	v_add_u32_e32 v149, 0x1800, v131
	global_load_dwordx2 v[234:235], v149, s[10:11]
	v_add_u32_e32 v132, 0x9800, v130
	global_load_dwordx2 v[236:237], v132, s[10:11]
	v_add_u32_e32 v149, 0x9800, v131
	global_load_dwordx2 v[238:239], v149, s[10:11]
	s_waitcnt vmcnt(31)
	v_pk_mul_f32 v[150:151], v[150:151], s[16:17] op_sel_hi:[1,0]
	v_fma_f32 v166, -v150, v150, v151
	v_max_f32_e32 v166, 0, v166
	v_add_f32_e32 v166, 0x3727c5ac, v166
	v_rsq_f32_e32 v166, v166
	v_mov_b32_e32 v245, 0
	v_mov_b32_e32 v246, 0
	s_waitcnt vmcnt(16)
	s_waitcnt vmcnt(15)
	v_lshlrev_b32_e32 v134, 16, v208
	v_and_b32_e32 v135, 0xffff0000, v208
	v_lshlrev_b32_e32 v136, 16, v209
	v_and_b32_e32 v137, 0xffff0000, v209
	v_pk_add_f32 v[134:135], v[134:135], v[150:151] op_sel_hi:[1,0] neg_lo:[0,1] neg_hi:[0,1]
	v_pk_add_f32 v[136:137], v[136:137], v[150:151] op_sel_hi:[1,0] neg_lo:[0,1] neg_hi:[0,1]
	v_pk_mul_f32 v[134:135], v[134:135], v[166:167] op_sel_hi:[1,0]
	v_pk_mul_f32 v[136:137], v[136:137], v[166:167] op_sel_hi:[1,0]
	v_pk_fma_f32 v[134:135], v[176:177], v[134:135], v[192:193]
	v_pk_fma_f32 v[136:137], v[178:179], v[136:137], v[194:195]
	v_pk_mul_f32 v[134:135], v[134:135], s[18:19] op_sel_hi:[1,0]
	v_pk_mul_f32 v[136:137], v[136:137], s[18:19] op_sel_hi:[1,0]
	v_pk_fma_f32 v[124:125], v[124:125], 0.5, v[134:135] op_sel_hi:[1,0,1]
	v_pk_fma_f32 v[126:127], v[126:127], 0.5, v[136:137] op_sel_hi:[1,0,1]
	v_add_f32_e32 v245, v245, v124
	v_fmac_f32_e32 v246, v124, v124
	v_add_f32_e32 v245, v245, v125
	v_fmac_f32_e32 v246, v125, v125
	v_add_f32_e32 v245, v245, v126
	v_fmac_f32_e32 v246, v126, v126
	v_add_f32_e32 v245, v245, v127
	v_fmac_f32_e32 v246, v127, v127
	s_waitcnt vmcnt(14)
	v_lshlrev_b32_e32 v240, 16, v210
	v_and_b32_e32 v241, 0xffff0000, v210
	v_lshlrev_b32_e32 v242, 16, v211
	v_and_b32_e32 v243, 0xffff0000, v211
	v_pk_add_f32 v[240:241], v[240:241], v[150:151] op_sel_hi:[1,0] neg_lo:[0,1] neg_hi:[0,1]
	v_pk_add_f32 v[242:243], v[242:243], v[150:151] op_sel_hi:[1,0] neg_lo:[0,1] neg_hi:[0,1]
	v_pk_mul_f32 v[240:241], v[240:241], v[166:167] op_sel_hi:[1,0]
	v_pk_mul_f32 v[242:243], v[242:243], v[166:167] op_sel_hi:[1,0]
	v_pk_fma_f32 v[240:241], v[180:181], v[240:241], v[196:197]
	v_pk_fma_f32 v[242:243], v[182:183], v[242:243], v[198:199]
	v_pk_mul_f32 v[240:241], v[240:241], s[18:19] op_sel_hi:[1,0]
	v_pk_mul_f32 v[242:243], v[242:243], s[18:19] op_sel_hi:[1,0]
	v_pk_fma_f32 v[120:121], v[120:121], 0.5, v[240:241] op_sel_hi:[1,0,1]
	v_pk_fma_f32 v[122:123], v[122:123], 0.5, v[242:243] op_sel_hi:[1,0,1]
	v_add_f32_e32 v245, v245, v120
	v_fmac_f32_e32 v246, v120, v120
	v_add_f32_e32 v245, v245, v121
	v_fmac_f32_e32 v246, v121, v121
	v_add_f32_e32 v245, v245, v122
	v_fmac_f32_e32 v246, v122, v122
	v_add_f32_e32 v245, v245, v123
	v_fmac_f32_e32 v246, v123, v123
	s_waitcnt vmcnt(13)
; template <int EPI>
; __device__ __forceinline__ void gemm_phase(const u16* __restrict__ A, const u16* __restrict__ Bt, const int K,
;                                            const int nN, char* shm, const EpiArgs& ea) {
;     ...
;                 for (int n = 0; n < 2; ++n) {
;                   const int col = cb + bj * 128 + n * 16;
;                   f32x4 c = acc[ai][bj][m][n];
;                   float h[4];
;                   if (EPI == EPI_FFN1) {
;                     float4 rv = *(const float4*)(ea.res + (size_t)row * DM + col);
;                     h[0] = rv.x; h[1] = rv.y; h[2] = rv.z; h[3] = rv.w;
;                   } else {
;                     uint2 yv = *(const uint2*)((const char*)ea.yb + tl_off(row, col, DM >> 6));
;                     float4 gv = *(const float4*)(ea.lng + col);
;                     float4 bv = *(const float4*)(ea.lnb + col);
;                     h[0] = (bf_lo(yv.x) - mu) * rstd * gv.x + bv.x; h[1] = (bf_hi(yv.x) - mu) * rstd * gv.y + bv.y;
;                     h[2] = (bf_lo(yv.y) - mu) * rstd * gv.z + bv.z; h[3] = (bf_hi(yv.y) - mu) * rstd * gv.w + bv.w;
;                   }
;                   float y[4];
;                   if (EPI == EPI_OUT) {
;                     float4 bo = *(const float4*)(ea.bias + col);
;                     y[0] = ALPHA * h[0] + c[0] + bo.x; y[1] = ALPHA * h[1] + c[1] + bo.y;
;                     y[2] = ALPHA * h[2] + c[2] + bo.z; y[3] = ALPHA * h[3] + c[3] + bo.w;
;                   } else {
; #pragma unroll
;                     for (int j = 0; j < 4; ++j) y[j] = ALPHA * h[j] + 0.5f * c[j];
;                   }
;                   if (EPI == EPI_FFN2) {
;                     *(float4*)(ea.outf + (size_t)row * DM + col) = make_float4(y[0], y[1], y[2], y[3]);
;                   } else {
;                     pk[n] = make_uint2(pack2(y[0], y[1]), pack2(y[2], y[3]));
;                     float q0 = bf_lo(pk[n].x), q1 = bf_hi(pk[n].x), q2 = bf_lo(pk[n].y), q3 = bf_hi(pk[n].y);
;                     rs += (q0 + q1) + (q2 + q3);
;                     rq += (q0 * q0 + q1 * q1) + (q2 * q2 + q3 * q3);
;                   }
;                 }
;                 if (EPI != EPI_FFN2) {
;                   const uint4 w = widen16(pk[0], pk[1]);
;                   *(uint4*)((char*)ea.yb + tl_off(row, cw + bj * 128, DM >> 6)) = w;
;                 }
;               }
	v_lshlrev_b32_e32 v134, 16, v212
	v_and_b32_e32 v135, 0xffff0000, v212
	v_lshlrev_b32_e32 v136, 16, v213
	v_and_b32_e32 v137, 0xffff0000, v213
	v_pk_add_f32 v[134:135], v[134:135], v[150:151] op_sel_hi:[1,0] neg_lo:[0,1] neg_hi:[0,1]
	v_pk_add_f32 v[136:137], v[136:137], v[150:151] op_sel_hi:[1,0] neg_lo:[0,1] neg_hi:[0,1]
	v_pk_mul_f32 v[134:135], v[134:135], v[166:167] op_sel_hi:[1,0]
	v_pk_mul_f32 v[136:137], v[136:137], v[166:167] op_sel_hi:[1,0]
	v_pk_fma_f32 v[134:135], v[184:185], v[134:135], v[200:201]
	v_pk_fma_f32 v[136:137], v[186:187], v[136:137], v[202:203]
	v_pk_mul_f32 v[134:135], v[134:135], s[18:19] op_sel_hi:[1,0]
	v_pk_mul_f32 v[136:137], v[136:137], s[18:19] op_sel_hi:[1,0]
	v_pk_fma_f32 v[116:117], v[116:117], 0.5, v[134:135] op_sel_hi:[1,0,1]
	v_pk_fma_f32 v[118:119], v[118:119], 0.5, v[136:137] op_sel_hi:[1,0,1]
	v_add_f32_e32 v245, v245, v116
	v_fmac_f32_e32 v246, v116, v116
	v_add_f32_e32 v245, v245, v117
	v_fmac_f32_e32 v246, v117, v117
	v_add_f32_e32 v245, v245, v118
	v_fmac_f32_e32 v246, v118, v118
	v_add_f32_e32 v245, v245, v119
	v_fmac_f32_e32 v246, v119, v119
	s_waitcnt vmcnt(12)
	v_lshlrev_b32_e32 v240, 16, v214
	v_and_b32_e32 v241, 0xffff0000, v214
	v_lshlrev_b32_e32 v242, 16, v215
	v_and_b32_e32 v243, 0xffff0000, v215
	v_pk_add_f32 v[240:241], v[240:241], v[150:151] op_sel_hi:[1,0] neg_lo:[0,1] neg_hi:[0,1]
	v_pk_add_f32 v[242:243], v[242:243], v[150:151] op_sel_hi:[1,0] neg_lo:[0,1] neg_hi:[0,1]
	v_pk_mul_f32 v[240:241], v[240:241], v[166:167] op_sel_hi:[1,0]
	v_pk_mul_f32 v[242:243], v[242:243], v[166:167] op_sel_hi:[1,0]
	v_pk_fma_f32 v[240:241], v[188:189], v[240:241], v[204:205]
	v_pk_fma_f32 v[242:243], v[190:191], v[242:243], v[206:207]
	v_pk_mul_f32 v[240:241], v[240:241], s[18:19] op_sel_hi:[1,0]
	v_pk_mul_f32 v[242:243], v[242:243], s[18:19] op_sel_hi:[1,0]
	v_pk_fma_f32 v[112:113], v[112:113], 0.5, v[240:241] op_sel_hi:[1,0,1]
	v_pk_fma_f32 v[114:115], v[114:115], 0.5, v[242:243] op_sel_hi:[1,0,1]
	v_add_f32_e32 v245, v245, v112
	v_fmac_f32_e32 v246, v112, v112
	v_add_f32_e32 v245, v245, v113
	v_fmac_f32_e32 v246, v113, v113
	v_add_f32_e32 v245, v245, v114
	v_fmac_f32_e32 v246, v114, v114
	v_add_f32_e32 v245, v245, v115
	v_fmac_f32_e32 v246, v115, v115
	v_add_u32_e32 v132, 0x84000, v130
	global_load_dwordx2 v[208:209], v132, s[10:11]
	v_add_u32_e32 v149, 0x84000, v131
	global_load_dwordx2 v[210:211], v149, s[10:11]
	v_add_u32_e32 v132, 0x8c000, v130
	global_load_dwordx2 v[212:213], v132, s[10:11]
	v_add_u32_e32 v149, 0x8c000, v131
	global_load_dwordx2 v[214:215], v149, s[10:11]
	v_mov_b32_e32 v247, v245
	v_mov_b32_e32 v248, v246
	s_nop 0
	v_permlane16_swap_b32_e32 v245, v247
	v_permlane16_swap_b32_e32 v246, v248
	v_add_f32_e32 v245, v245, v247
	v_add_f32_e32 v246, v246, v248
	v_mov_b32_e32 v247, v245
	v_mov_b32_e32 v248, v246
	s_nop 0
	v_permlane32_swap_b32_e32 v245, v247
	v_permlane32_swap_b32_e32 v246, v248
	v_add_f32_e32 v245, v245, v247
	v_add_f32_e32 v246, v246, v248
	v_and_b32_e32 v132, 48, v174
	v_cmp_eq_u32_e32 vcc, 0, v132
	s_and_saveexec_b64 s[98:99], vcc
	global_atomic_add_f32 v252, v245, s[90:91]
	global_atomic_add_f32 v252, v246, s[90:91] offset:4
	s_or_b64 exec, exec, s[98:99]
	v_pk_mul_f32 v[152:153], v[152:153], s[16:17] op_sel_hi:[1,0]
	v_fma_f32 v168, -v152, v152, v153
	v_max_f32_e32 v168, 0, v168
	v_add_f32_e32 v168, 0x3727c5ac, v168
	v_rsq_f32_e32 v168, v168
	v_mov_b32_e32 v245, 0
	v_mov_b32_e32 v246, 0
	s_waitcnt vmcnt(17)
	v_lshlrev_b32_e32 v134, 16, v216
	v_and_b32_e32 v135, 0xffff0000, v216
	v_lshlrev_b32_e32 v136, 16, v217
	v_and_b32_e32 v137, 0xffff0000, v217
	v_pk_add_f32 v[134:135], v[134:135], v[152:153] op_sel_hi:[1,0] neg_lo:[0,1] neg_hi:[0,1]
	v_pk_add_f32 v[136:137], v[136:137], v[152:153] op_sel_hi:[1,0] neg_lo:[0,1] neg_hi:[0,1]
	v_pk_mul_f32 v[134:135], v[134:135], v[168:169] op_sel_hi:[1,0]
	v_pk_mul_f32 v[136:137], v[136:137], v[168:169] op_sel_hi:[1,0]
	v_pk_fma_f32 v[134:135], v[176:177], v[134:135], v[192:193]
	v_pk_fma_f32 v[136:137], v[178:179], v[136:137], v[194:195]
	v_pk_mul_f32 v[134:135], v[134:135], s[18:19] op_sel_hi:[1,0]
	v_pk_mul_f32 v[136:137], v[136:137], s[18:19] op_sel_hi:[1,0]
	v_pk_fma_f32 v[108:109], v[108:109], 0.5, v[134:135] op_sel_hi:[1,0,1]
	v_pk_fma_f32 v[110:111], v[110:111], 0.5, v[136:137] op_sel_hi:[1,0,1]
	v_add_f32_e32 v245, v245, v108
	v_fmac_f32_e32 v246, v108, v108
	v_add_f32_e32 v245, v245, v109
	v_fmac_f32_e32 v246, v109, v109
	v_add_f32_e32 v245, v245, v110
	v_fmac_f32_e32 v246, v110, v110
	v_add_f32_e32 v245, v245, v111
	v_fmac_f32_e32 v246, v111, v111
	s_waitcnt vmcnt(16)
	v_lshlrev_b32_e32 v240, 16, v218
	v_and_b32_e32 v241, 0xffff0000, v218
	v_lshlrev_b32_e32 v242, 16, v219
	v_and_b32_e32 v243, 0xffff0000, v219
	v_pk_add_f32 v[240:241], v[240:241], v[152:153] op_sel_hi:[1,0] neg_lo:[0,1] neg_hi:[0,1]
	v_pk_add_f32 v[242:243], v[242:243], v[152:153] op_sel_hi:[1,0] neg_lo:[0,1] neg_hi:[0,1]
	v_pk_mul_f32 v[240:241], v[240:241], v[168:169] op_sel_hi:[1,0]
	v_pk_mul_f32 v[242:243], v[242:243], v[168:169] op_sel_hi:[1,0]
	v_pk_fma_f32 v[240:241], v[180:181], v[240:241], v[196:197]
	v_pk_fma_f32 v[242:243], v[182:183], v[242:243], v[198:199]
	v_pk_mul_f32 v[240:241], v[240:241], s[18:19] op_sel_hi:[1,0]
	v_pk_mul_f32 v[242:243], v[242:243], s[18:19] op_sel_hi:[1,0]
	v_pk_fma_f32 v[104:105], v[104:105], 0.5, v[240:241] op_sel_hi:[1,0,1]
	v_pk_fma_f32 v[106:107], v[106:107], 0.5, v[242:243] op_sel_hi:[1,0,1]
	v_add_f32_e32 v245, v245, v104
	v_fmac_f32_e32 v246, v104, v104
	v_add_f32_e32 v245, v245, v105
	v_fmac_f32_e32 v246, v105, v105
	v_add_f32_e32 v245, v245, v106
	v_fmac_f32_e32 v246, v106, v106
	v_add_f32_e32 v245, v245, v107
	v_fmac_f32_e32 v246, v107, v107
	s_waitcnt vmcnt(15)
; template <int EPI>
; __device__ __forceinline__ void gemm_phase(const u16* __restrict__ A, const u16* __restrict__ Bt, const int K,
;                                            const int nN, char* shm, const EpiArgs& ea) {
;     ...
;                 for (int n = 0; n < 2; ++n) {
;                   const int col = cb + bj * 128 + n * 16;
;                   f32x4 c = acc[ai][bj][m][n];
;                   float h[4];
;                   if (EPI == EPI_FFN1) {
;                     float4 rv = *(const float4*)(ea.res + (size_t)row * DM + col);
;                     h[0] = rv.x; h[1] = rv.y; h[2] = rv.z; h[3] = rv.w;
;                   } else {
;                     uint2 yv = *(const uint2*)((const char*)ea.yb + tl_off(row, col, DM >> 6));
;                     float4 gv = *(const float4*)(ea.lng + col);
;                     float4 bv = *(const float4*)(ea.lnb + col);
;                     h[0] = (bf_lo(yv.x) - mu) * rstd * gv.x + bv.x; h[1] = (bf_hi(yv.x) - mu) * rstd * gv.y + bv.y;
;                     h[2] = (bf_lo(yv.y) - mu) * rstd * gv.z + bv.z; h[3] = (bf_hi(yv.y) - mu) * rstd * gv.w + bv.w;
;                   }
;                   float y[4];
;                   if (EPI == EPI_OUT) {
;                     float4 bo = *(const float4*)(ea.bias + col);
;                     y[0] = ALPHA * h[0] + c[0] + bo.x; y[1] = ALPHA * h[1] + c[1] + bo.y;
;                     y[2] = ALPHA * h[2] + c[2] + bo.z; y[3] = ALPHA * h[3] + c[3] + bo.w;
;                   } else {
; #pragma unroll
;                     for (int j = 0; j < 4; ++j) y[j] = ALPHA * h[j] + 0.5f * c[j];
;                   }
;                   if (EPI == EPI_FFN2) {
;                     *(float4*)(ea.outf + (size_t)row * DM + col) = make_float4(y[0], y[1], y[2], y[3]);
;                   } else {
;                     pk[n] = make_uint2(pack2(y[0], y[1]), pack2(y[2], y[3]));
;                     float q0 = bf_lo(pk[n].x), q1 = bf_hi(pk[n].x), q2 = bf_lo(pk[n].y), q3 = bf_hi(pk[n].y);
;                     rs += (q0 + q1) + (q2 + q3);
;                     rq += (q0 * q0 + q1 * q1) + (q2 * q2 + q3 * q3);
;                   }
;                 }
;                 if (EPI != EPI_FFN2) {
;                   const uint4 w = widen16(pk[0], pk[1]);
;                   *(uint4*)((char*)ea.yb + tl_off(row, cw + bj * 128, DM >> 6)) = w;
;                 }
;               }
	v_lshlrev_b32_e32 v134, 16, v220
	v_and_b32_e32 v135, 0xffff0000, v220
	v_lshlrev_b32_e32 v136, 16, v221
	v_and_b32_e32 v137, 0xffff0000, v221
	v_pk_add_f32 v[134:135], v[134:135], v[152:153] op_sel_hi:[1,0] neg_lo:[0,1] neg_hi:[0,1]
	v_pk_add_f32 v[136:137], v[136:137], v[152:153] op_sel_hi:[1,0] neg_lo:[0,1] neg_hi:[0,1]
	v_pk_mul_f32 v[134:135], v[134:135], v[168:169] op_sel_hi:[1,0]
	v_pk_mul_f32 v[136:137], v[136:137], v[168:169] op_sel_hi:[1,0]
	v_pk_fma_f32 v[134:135], v[184:185], v[134:135], v[200:201]
	v_pk_fma_f32 v[136:137], v[186:187], v[136:137], v[202:203]
	v_pk_mul_f32 v[134:135], v[134:135], s[18:19] op_sel_hi:[1,0]
	v_pk_mul_f32 v[136:137], v[136:137], s[18:19] op_sel_hi:[1,0]
	v_pk_fma_f32 v[100:101], v[100:101], 0.5, v[134:135] op_sel_hi:[1,0,1]
	v_pk_fma_f32 v[102:103], v[102:103], 0.5, v[136:137] op_sel_hi:[1,0,1]
	v_add_f32_e32 v245, v245, v100
	v_fmac_f32_e32 v246, v100, v100
	v_add_f32_e32 v245, v245, v101
	v_fmac_f32_e32 v246, v101, v101
	v_add_f32_e32 v245, v245, v102
	v_fmac_f32_e32 v246, v102, v102
	v_add_f32_e32 v245, v245, v103
	v_fmac_f32_e32 v246, v103, v103
	s_waitcnt vmcnt(14)
	v_lshlrev_b32_e32 v240, 16, v222
	v_and_b32_e32 v241, 0xffff0000, v222
	v_lshlrev_b32_e32 v242, 16, v223
	v_and_b32_e32 v243, 0xffff0000, v223
	v_pk_add_f32 v[240:241], v[240:241], v[152:153] op_sel_hi:[1,0] neg_lo:[0,1] neg_hi:[0,1]
	v_pk_add_f32 v[242:243], v[242:243], v[152:153] op_sel_hi:[1,0] neg_lo:[0,1] neg_hi:[0,1]
	v_pk_mul_f32 v[240:241], v[240:241], v[168:169] op_sel_hi:[1,0]
	v_pk_mul_f32 v[242:243], v[242:243], v[168:169] op_sel_hi:[1,0]
	v_pk_fma_f32 v[240:241], v[188:189], v[240:241], v[204:205]
	v_pk_fma_f32 v[242:243], v[190:191], v[242:243], v[206:207]
	v_pk_mul_f32 v[240:241], v[240:241], s[18:19] op_sel_hi:[1,0]
	v_pk_mul_f32 v[242:243], v[242:243], s[18:19] op_sel_hi:[1,0]
	v_pk_fma_f32 v[96:97], v[96:97], 0.5, v[240:241] op_sel_hi:[1,0,1]
	v_pk_fma_f32 v[98:99], v[98:99], 0.5, v[242:243] op_sel_hi:[1,0,1]
	v_add_f32_e32 v245, v245, v96
	v_fmac_f32_e32 v246, v96, v96
	v_add_f32_e32 v245, v245, v97
	v_fmac_f32_e32 v246, v97, v97
	v_add_f32_e32 v245, v245, v98
	v_fmac_f32_e32 v246, v98, v98
	v_add_f32_e32 v245, v245, v99
	v_fmac_f32_e32 v246, v99, v99
	v_add_u32_e32 v132, 0x84800, v130
	global_load_dwordx2 v[216:217], v132, s[10:11]
	v_add_u32_e32 v149, 0x84800, v131
	global_load_dwordx2 v[218:219], v149, s[10:11]
	v_add_u32_e32 v132, 0x8c800, v130
	global_load_dwordx2 v[220:221], v132, s[10:11]
	v_add_u32_e32 v149, 0x8c800, v131
	global_load_dwordx2 v[222:223], v149, s[10:11]
	v_mov_b32_e32 v247, v245
	v_mov_b32_e32 v248, v246
	s_nop 0
	v_permlane16_swap_b32_e32 v245, v247
	v_permlane16_swap_b32_e32 v246, v248
	v_add_f32_e32 v245, v245, v247
	v_add_f32_e32 v246, v246, v248
	v_mov_b32_e32 v247, v245
	v_mov_b32_e32 v248, v246
	s_nop 0
	v_permlane32_swap_b32_e32 v245, v247
	v_permlane32_swap_b32_e32 v246, v248
	v_add_f32_e32 v245, v245, v247
	v_add_f32_e32 v246, v246, v248
	v_and_b32_e32 v132, 48, v174
	v_cmp_eq_u32_e32 vcc, 0, v132
	s_and_saveexec_b64 s[98:99], vcc
	global_atomic_add_f32 v252, v245, s[90:91] offset:128
	global_atomic_add_f32 v252, v246, s[90:91] offset:132
	s_or_b64 exec, exec, s[98:99]
	v_pk_mul_f32 v[154:155], v[154:155], s[16:17] op_sel_hi:[1,0]
	v_fma_f32 v166, -v154, v154, v155
	v_max_f32_e32 v166, 0, v166
	v_add_f32_e32 v166, 0x3727c5ac, v166
	v_rsq_f32_e32 v166, v166
	v_mov_b32_e32 v245, 0
	v_mov_b32_e32 v246, 0
	s_waitcnt vmcnt(19)
	v_lshlrev_b32_e32 v134, 16, v224
	v_and_b32_e32 v135, 0xffff0000, v224
	v_lshlrev_b32_e32 v136, 16, v225
	v_and_b32_e32 v137, 0xffff0000, v225
	v_pk_add_f32 v[134:135], v[134:135], v[154:155] op_sel_hi:[1,0] neg_lo:[0,1] neg_hi:[0,1]
	v_pk_add_f32 v[136:137], v[136:137], v[154:155] op_sel_hi:[1,0] neg_lo:[0,1] neg_hi:[0,1]
	v_pk_mul_f32 v[134:135], v[134:135], v[166:167] op_sel_hi:[1,0]
	v_pk_mul_f32 v[136:137], v[136:137], v[166:167] op_sel_hi:[1,0]
	v_pk_fma_f32 v[134:135], v[176:177], v[134:135], v[192:193]
	v_pk_fma_f32 v[136:137], v[178:179], v[136:137], v[194:195]
	v_pk_mul_f32 v[134:135], v[134:135], s[18:19] op_sel_hi:[1,0]
	v_pk_mul_f32 v[136:137], v[136:137], s[18:19] op_sel_hi:[1,0]
	v_pk_fma_f32 v[92:93], v[92:93], 0.5, v[134:135] op_sel_hi:[1,0,1]
	v_pk_fma_f32 v[94:95], v[94:95], 0.5, v[136:137] op_sel_hi:[1,0,1]
	v_add_f32_e32 v245, v245, v92
	v_fmac_f32_e32 v246, v92, v92
	v_add_f32_e32 v245, v245, v93
	v_fmac_f32_e32 v246, v93, v93
	v_add_f32_e32 v245, v245, v94
	v_fmac_f32_e32 v246, v94, v94
	v_add_f32_e32 v245, v245, v95
	v_fmac_f32_e32 v246, v95, v95
	s_waitcnt vmcnt(18)
	v_lshlrev_b32_e32 v240, 16, v226
	v_and_b32_e32 v241, 0xffff0000, v226
	v_lshlrev_b32_e32 v242, 16, v227
	v_and_b32_e32 v243, 0xffff0000, v227
	v_pk_add_f32 v[240:241], v[240:241], v[154:155] op_sel_hi:[1,0] neg_lo:[0,1] neg_hi:[0,1]
	v_pk_add_f32 v[242:243], v[242:243], v[154:155] op_sel_hi:[1,0] neg_lo:[0,1] neg_hi:[0,1]
	v_pk_mul_f32 v[240:241], v[240:241], v[166:167] op_sel_hi:[1,0]
	v_pk_mul_f32 v[242:243], v[242:243], v[166:167] op_sel_hi:[1,0]
	v_pk_fma_f32 v[240:241], v[180:181], v[240:241], v[196:197]
	v_pk_fma_f32 v[242:243], v[182:183], v[242:243], v[198:199]
	v_pk_mul_f32 v[240:241], v[240:241], s[18:19] op_sel_hi:[1,0]
	v_pk_mul_f32 v[242:243], v[242:243], s[18:19] op_sel_hi:[1,0]
	v_pk_fma_f32 v[88:89], v[88:89], 0.5, v[240:241] op_sel_hi:[1,0,1]
	v_pk_fma_f32 v[90:91], v[90:91], 0.5, v[242:243] op_sel_hi:[1,0,1]
	v_add_f32_e32 v245, v245, v88
	v_fmac_f32_e32 v246, v88, v88
	v_add_f32_e32 v245, v245, v89
	v_fmac_f32_e32 v246, v89, v89
	v_add_f32_e32 v245, v245, v90
	v_fmac_f32_e32 v246, v90, v90
	v_add_f32_e32 v245, v245, v91
	v_fmac_f32_e32 v246, v91, v91
	s_waitcnt vmcnt(17)
; template <int EPI>
; __device__ __forceinline__ void gemm_phase(const u16* __restrict__ A, const u16* __restrict__ Bt, const int K,
;                                            const int nN, char* shm, const EpiArgs& ea) {
;     ...
;                 for (int n = 0; n < 2; ++n) {
;                   const int col = cb + bj * 128 + n * 16;
;                   f32x4 c = acc[ai][bj][m][n];
;                   float h[4];
;                   if (EPI == EPI_FFN1) {
;                     float4 rv = *(const float4*)(ea.res + (size_t)row * DM + col);
;                     h[0] = rv.x; h[1] = rv.y; h[2] = rv.z; h[3] = rv.w;
;                   } else {
;                     uint2 yv = *(const uint2*)((const char*)ea.yb + tl_off(row, col, DM >> 6));
;                     float4 gv = *(const float4*)(ea.lng + col);
;                     float4 bv = *(const float4*)(ea.lnb + col);
;                     h[0] = (bf_lo(yv.x) - mu) * rstd * gv.x + bv.x; h[1] = (bf_hi(yv.x) - mu) * rstd * gv.y + bv.y;
;                     h[2] = (bf_lo(yv.y) - mu) * rstd * gv.z + bv.z; h[3] = (bf_hi(yv.y) - mu) * rstd * gv.w + bv.w;
;                   }
;                   float y[4];
;                   if (EPI == EPI_OUT) {
;                     float4 bo = *(const float4*)(ea.bias + col);
;                     y[0] = ALPHA * h[0] + c[0] + bo.x; y[1] = ALPHA * h[1] + c[1] + bo.y;
;                     y[2] = ALPHA * h[2] + c[2] + bo.z; y[3] = ALPHA * h[3] + c[3] + bo.w;
;                   } else {
; #pragma unroll
;                     for (int j = 0; j < 4; ++j) y[j] = ALPHA * h[j] + 0.5f * c[j];
;                   }
;                   if (EPI == EPI_FFN2) {
;                     *(float4*)(ea.outf + (size_t)row * DM + col) = make_float4(y[0], y[1], y[2], y[3]);
;                   } else {
;                     pk[n] = make_uint2(pack2(y[0], y[1]), pack2(y[2], y[3]));
;                     float q0 = bf_lo(pk[n].x), q1 = bf_hi(pk[n].x), q2 = bf_lo(pk[n].y), q3 = bf_hi(pk[n].y);
;                     rs += (q0 + q1) + (q2 + q3);
;                     rq += (q0 * q0 + q1 * q1) + (q2 * q2 + q3 * q3);
;                   }
;                 }
;                 if (EPI != EPI_FFN2) {
;                   const uint4 w = widen16(pk[0], pk[1]);
;                   *(uint4*)((char*)ea.yb + tl_off(row, cw + bj * 128, DM >> 6)) = w;
;                 }
;               }
	v_lshlrev_b32_e32 v134, 16, v228
	v_and_b32_e32 v135, 0xffff0000, v228
	v_lshlrev_b32_e32 v136, 16, v229
	v_and_b32_e32 v137, 0xffff0000, v229
	v_pk_add_f32 v[134:135], v[134:135], v[154:155] op_sel_hi:[1,0] neg_lo:[0,1] neg_hi:[0,1]
	v_pk_add_f32 v[136:137], v[136:137], v[154:155] op_sel_hi:[1,0] neg_lo:[0,1] neg_hi:[0,1]
	v_pk_mul_f32 v[134:135], v[134:135], v[166:167] op_sel_hi:[1,0]
	v_pk_mul_f32 v[136:137], v[136:137], v[166:167] op_sel_hi:[1,0]
	v_pk_fma_f32 v[134:135], v[184:185], v[134:135], v[200:201]
	v_pk_fma_f32 v[136:137], v[186:187], v[136:137], v[202:203]
	v_pk_mul_f32 v[134:135], v[134:135], s[18:19] op_sel_hi:[1,0]
	v_pk_mul_f32 v[136:137], v[136:137], s[18:19] op_sel_hi:[1,0]
	v_pk_fma_f32 v[84:85], v[84:85], 0.5, v[134:135] op_sel_hi:[1,0,1]
	v_pk_fma_f32 v[86:87], v[86:87], 0.5, v[136:137] op_sel_hi:[1,0,1]
	v_add_f32_e32 v245, v245, v84
	v_fmac_f32_e32 v246, v84, v84
	v_add_f32_e32 v245, v245, v85
	v_fmac_f32_e32 v246, v85, v85
	v_add_f32_e32 v245, v245, v86
	v_fmac_f32_e32 v246, v86, v86
	v_add_f32_e32 v245, v245, v87
	v_fmac_f32_e32 v246, v87, v87
	s_waitcnt vmcnt(16)
	v_lshlrev_b32_e32 v240, 16, v230
	v_and_b32_e32 v241, 0xffff0000, v230
	v_lshlrev_b32_e32 v242, 16, v231
	v_and_b32_e32 v243, 0xffff0000, v231
	v_pk_add_f32 v[240:241], v[240:241], v[154:155] op_sel_hi:[1,0] neg_lo:[0,1] neg_hi:[0,1]
	v_pk_add_f32 v[242:243], v[242:243], v[154:155] op_sel_hi:[1,0] neg_lo:[0,1] neg_hi:[0,1]
	v_pk_mul_f32 v[240:241], v[240:241], v[166:167] op_sel_hi:[1,0]
	v_pk_mul_f32 v[242:243], v[242:243], v[166:167] op_sel_hi:[1,0]
	v_pk_fma_f32 v[240:241], v[188:189], v[240:241], v[204:205]
	v_pk_fma_f32 v[242:243], v[190:191], v[242:243], v[206:207]
	v_pk_mul_f32 v[240:241], v[240:241], s[18:19] op_sel_hi:[1,0]
	v_pk_mul_f32 v[242:243], v[242:243], s[18:19] op_sel_hi:[1,0]
	v_pk_fma_f32 v[80:81], v[80:81], 0.5, v[240:241] op_sel_hi:[1,0,1]
	v_pk_fma_f32 v[82:83], v[82:83], 0.5, v[242:243] op_sel_hi:[1,0,1]
	v_add_f32_e32 v245, v245, v80
	v_fmac_f32_e32 v246, v80, v80
	v_add_f32_e32 v245, v245, v81
	v_fmac_f32_e32 v246, v81, v81
	v_add_f32_e32 v245, v245, v82
	v_fmac_f32_e32 v246, v82, v82
	v_add_f32_e32 v245, v245, v83
	v_fmac_f32_e32 v246, v83, v83
	v_add_u32_e32 v132, 0x85000, v130
	global_load_dwordx2 v[224:225], v132, s[10:11]
	v_add_u32_e32 v149, 0x85000, v131
	global_load_dwordx2 v[226:227], v149, s[10:11]
	v_add_u32_e32 v132, 0x8d000, v130
	global_load_dwordx2 v[228:229], v132, s[10:11]
	v_add_u32_e32 v149, 0x8d000, v131
	global_load_dwordx2 v[230:231], v149, s[10:11]
	v_mov_b32_e32 v247, v245
	v_mov_b32_e32 v248, v246
	s_nop 0
	v_permlane16_swap_b32_e32 v245, v247
	v_permlane16_swap_b32_e32 v246, v248
	v_add_f32_e32 v245, v245, v247
	v_add_f32_e32 v246, v246, v248
	v_mov_b32_e32 v247, v245
	v_mov_b32_e32 v248, v246
	s_nop 0
	v_permlane32_swap_b32_e32 v245, v247
	v_permlane32_swap_b32_e32 v246, v248
	v_add_f32_e32 v245, v245, v247
	v_add_f32_e32 v246, v246, v248
	v_and_b32_e32 v132, 48, v174
	v_cmp_eq_u32_e32 vcc, 0, v132
	s_and_saveexec_b64 s[98:99], vcc
	global_atomic_add_f32 v252, v245, s[90:91] offset:256
	global_atomic_add_f32 v252, v246, s[90:91] offset:260
	s_or_b64 exec, exec, s[98:99]
	v_pk_mul_f32 v[156:157], v[156:157], s[16:17] op_sel_hi:[1,0]
	v_fma_f32 v168, -v156, v156, v157
	v_max_f32_e32 v168, 0, v168
	v_add_f32_e32 v168, 0x3727c5ac, v168
	v_rsq_f32_e32 v168, v168
	v_mov_b32_e32 v245, 0
	v_mov_b32_e32 v246, 0
	s_waitcnt vmcnt(21)
	v_lshlrev_b32_e32 v134, 16, v232
	v_and_b32_e32 v135, 0xffff0000, v232
	v_lshlrev_b32_e32 v136, 16, v233
	v_and_b32_e32 v137, 0xffff0000, v233
	v_pk_add_f32 v[134:135], v[134:135], v[156:157] op_sel_hi:[1,0] neg_lo:[0,1] neg_hi:[0,1]
	v_pk_add_f32 v[136:137], v[136:137], v[156:157] op_sel_hi:[1,0] neg_lo:[0,1] neg_hi:[0,1]
	v_pk_mul_f32 v[134:135], v[134:135], v[168:169] op_sel_hi:[1,0]
	v_pk_mul_f32 v[136:137], v[136:137], v[168:169] op_sel_hi:[1,0]
	v_pk_fma_f32 v[134:135], v[176:177], v[134:135], v[192:193]
	v_pk_fma_f32 v[136:137], v[178:179], v[136:137], v[194:195]
	v_pk_mul_f32 v[134:135], v[134:135], s[18:19] op_sel_hi:[1,0]
	v_pk_mul_f32 v[136:137], v[136:137], s[18:19] op_sel_hi:[1,0]
	v_pk_fma_f32 v[76:77], v[76:77], 0.5, v[134:135] op_sel_hi:[1,0,1]
	v_pk_fma_f32 v[78:79], v[78:79], 0.5, v[136:137] op_sel_hi:[1,0,1]
	v_add_f32_e32 v245, v245, v76
	v_fmac_f32_e32 v246, v76, v76
	v_add_f32_e32 v245, v245, v77
	v_fmac_f32_e32 v246, v77, v77
	v_add_f32_e32 v245, v245, v78
	v_fmac_f32_e32 v246, v78, v78
	v_add_f32_e32 v245, v245, v79
	v_fmac_f32_e32 v246, v79, v79
	s_waitcnt vmcnt(20)
	v_lshlrev_b32_e32 v240, 16, v234
	v_and_b32_e32 v241, 0xffff0000, v234
	v_lshlrev_b32_e32 v242, 16, v235
	v_and_b32_e32 v243, 0xffff0000, v235
	v_pk_add_f32 v[240:241], v[240:241], v[156:157] op_sel_hi:[1,0] neg_lo:[0,1] neg_hi:[0,1]
	v_pk_add_f32 v[242:243], v[242:243], v[156:157] op_sel_hi:[1,0] neg_lo:[0,1] neg_hi:[0,1]
	v_pk_mul_f32 v[240:241], v[240:241], v[168:169] op_sel_hi:[1,0]
	v_pk_mul_f32 v[242:243], v[242:243], v[168:169] op_sel_hi:[1,0]
	v_pk_fma_f32 v[240:241], v[180:181], v[240:241], v[196:197]
	v_pk_fma_f32 v[242:243], v[182:183], v[242:243], v[198:199]
	v_pk_mul_f32 v[240:241], v[240:241], s[18:19] op_sel_hi:[1,0]
	v_pk_mul_f32 v[242:243], v[242:243], s[18:19] op_sel_hi:[1,0]
	v_pk_fma_f32 v[72:73], v[72:73], 0.5, v[240:241] op_sel_hi:[1,0,1]
	v_pk_fma_f32 v[74:75], v[74:75], 0.5, v[242:243] op_sel_hi:[1,0,1]
	v_add_f32_e32 v245, v245, v72
	v_fmac_f32_e32 v246, v72, v72
	v_add_f32_e32 v245, v245, v73
	v_fmac_f32_e32 v246, v73, v73
	v_add_f32_e32 v245, v245, v74
	v_fmac_f32_e32 v246, v74, v74
	v_add_f32_e32 v245, v245, v75
	v_fmac_f32_e32 v246, v75, v75
	s_waitcnt vmcnt(19)
; template <int EPI>
; __device__ __forceinline__ void gemm_phase(const u16* __restrict__ A, const u16* __restrict__ Bt, const int K,
;                                            const int nN, char* shm, const EpiArgs& ea) {
;     ...
;                 for (int n = 0; n < 2; ++n) {
;                   const int col = cb + bj * 128 + n * 16;
;                   f32x4 c = acc[ai][bj][m][n];
;                   float h[4];
;                   if (EPI == EPI_FFN1) {
;                     float4 rv = *(const float4*)(ea.res + (size_t)row * DM + col);
;                     h[0] = rv.x; h[1] = rv.y; h[2] = rv.z; h[3] = rv.w;
;                   } else {
;                     uint2 yv = *(const uint2*)((const char*)ea.yb + tl_off(row, col, DM >> 6));
;                     float4 gv = *(const float4*)(ea.lng + col);
;                     float4 bv = *(const float4*)(ea.lnb + col);
;                     h[0] = (bf_lo(yv.x) - mu) * rstd * gv.x + bv.x; h[1] = (bf_hi(yv.x) - mu) * rstd * gv.y + bv.y;
;                     h[2] = (bf_lo(yv.y) - mu) * rstd * gv.z + bv.z; h[3] = (bf_hi(yv.y) - mu) * rstd * gv.w + bv.w;
;                   }
;                   float y[4];
;                   if (EPI == EPI_OUT) {
;                     float4 bo = *(const float4*)(ea.bias + col);
;                     y[0] = ALPHA * h[0] + c[0] + bo.x; y[1] = ALPHA * h[1] + c[1] + bo.y;
;                     y[2] = ALPHA * h[2] + c[2] + bo.z; y[3] = ALPHA * h[3] + c[3] + bo.w;
;                   } else {
; #pragma unroll
;                     for (int j = 0; j < 4; ++j) y[j] = ALPHA * h[j] + 0.5f * c[j];
;                   }
;                   if (EPI == EPI_FFN2) {
;                     *(float4*)(ea.outf + (size_t)row * DM + col) = make_float4(y[0], y[1], y[2], y[3]);
;                   } else {
;                     pk[n] = make_uint2(pack2(y[0], y[1]), pack2(y[2], y[3]));
;                     float q0 = bf_lo(pk[n].x), q1 = bf_hi(pk[n].x), q2 = bf_lo(pk[n].y), q3 = bf_hi(pk[n].y);
;                     rs += (q0 + q1) + (q2 + q3);
;                     rq += (q0 * q0 + q1 * q1) + (q2 * q2 + q3 * q3);
;                   }
;                 }
;                 if (EPI != EPI_FFN2) {
;                   const uint4 w = widen16(pk[0], pk[1]);
;                   *(uint4*)((char*)ea.yb + tl_off(row, cw + bj * 128, DM >> 6)) = w;
;                 }
;               }
	v_lshlrev_b32_e32 v134, 16, v236
	v_and_b32_e32 v135, 0xffff0000, v236
	v_lshlrev_b32_e32 v136, 16, v237
	v_and_b32_e32 v137, 0xffff0000, v237
	v_pk_add_f32 v[134:135], v[134:135], v[156:157] op_sel_hi:[1,0] neg_lo:[0,1] neg_hi:[0,1]
	v_pk_add_f32 v[136:137], v[136:137], v[156:157] op_sel_hi:[1,0] neg_lo:[0,1] neg_hi:[0,1]
	v_pk_mul_f32 v[134:135], v[134:135], v[168:169] op_sel_hi:[1,0]
	v_pk_mul_f32 v[136:137], v[136:137], v[168:169] op_sel_hi:[1,0]
	v_pk_fma_f32 v[134:135], v[184:185], v[134:135], v[200:201]
	v_pk_fma_f32 v[136:137], v[186:187], v[136:137], v[202:203]
	v_pk_mul_f32 v[134:135], v[134:135], s[18:19] op_sel_hi:[1,0]
	v_pk_mul_f32 v[136:137], v[136:137], s[18:19] op_sel_hi:[1,0]
	v_pk_fma_f32 v[68:69], v[68:69], 0.5, v[134:135] op_sel_hi:[1,0,1]
	v_pk_fma_f32 v[70:71], v[70:71], 0.5, v[136:137] op_sel_hi:[1,0,1]
	v_add_f32_e32 v245, v245, v68
	v_fmac_f32_e32 v246, v68, v68
	v_add_f32_e32 v245, v245, v69
	v_fmac_f32_e32 v246, v69, v69
	v_add_f32_e32 v245, v245, v70
	v_fmac_f32_e32 v246, v70, v70
	v_add_f32_e32 v245, v245, v71
	v_fmac_f32_e32 v246, v71, v71
	s_waitcnt vmcnt(18)
	v_lshlrev_b32_e32 v240, 16, v238
	v_and_b32_e32 v241, 0xffff0000, v238
	v_lshlrev_b32_e32 v242, 16, v239
	v_and_b32_e32 v243, 0xffff0000, v239
	v_pk_add_f32 v[240:241], v[240:241], v[156:157] op_sel_hi:[1,0] neg_lo:[0,1] neg_hi:[0,1]
	v_pk_add_f32 v[242:243], v[242:243], v[156:157] op_sel_hi:[1,0] neg_lo:[0,1] neg_hi:[0,1]
	v_pk_mul_f32 v[240:241], v[240:241], v[168:169] op_sel_hi:[1,0]
	v_pk_mul_f32 v[242:243], v[242:243], v[168:169] op_sel_hi:[1,0]
	v_pk_fma_f32 v[240:241], v[188:189], v[240:241], v[204:205]
	v_pk_fma_f32 v[242:243], v[190:191], v[242:243], v[206:207]
	v_pk_mul_f32 v[240:241], v[240:241], s[18:19] op_sel_hi:[1,0]
	v_pk_mul_f32 v[242:243], v[242:243], s[18:19] op_sel_hi:[1,0]
	v_pk_fma_f32 v[64:65], v[64:65], 0.5, v[240:241] op_sel_hi:[1,0,1]
	v_pk_fma_f32 v[66:67], v[66:67], 0.5, v[242:243] op_sel_hi:[1,0,1]
	v_add_f32_e32 v245, v245, v64
	v_fmac_f32_e32 v246, v64, v64
	v_add_f32_e32 v245, v245, v65
	v_fmac_f32_e32 v246, v65, v65
	v_add_f32_e32 v245, v245, v66
	v_fmac_f32_e32 v246, v66, v66
	v_add_f32_e32 v245, v245, v67
	v_fmac_f32_e32 v246, v67, v67
	v_add_u32_e32 v132, 0x85800, v130
	global_load_dwordx2 v[232:233], v132, s[10:11]
	v_add_u32_e32 v149, 0x85800, v131
	global_load_dwordx2 v[234:235], v149, s[10:11]
	v_add_u32_e32 v132, 0x8d800, v130
	global_load_dwordx2 v[236:237], v132, s[10:11]
	v_add_u32_e32 v149, 0x8d800, v131
	global_load_dwordx2 v[238:239], v149, s[10:11]
	v_mov_b32_e32 v247, v245
	v_mov_b32_e32 v248, v246
	s_nop 0
	v_permlane16_swap_b32_e32 v245, v247
	v_permlane16_swap_b32_e32 v246, v248
	v_add_f32_e32 v245, v245, v247
	v_add_f32_e32 v246, v246, v248
	v_mov_b32_e32 v247, v245
	v_mov_b32_e32 v248, v246
	s_nop 0
	v_permlane32_swap_b32_e32 v245, v247
	v_permlane32_swap_b32_e32 v246, v248
	v_add_f32_e32 v245, v245, v247
	v_add_f32_e32 v246, v246, v248
	v_and_b32_e32 v132, 48, v174
	v_cmp_eq_u32_e32 vcc, 0, v132
	s_and_saveexec_b64 s[98:99], vcc
	global_atomic_add_f32 v252, v245, s[90:91] offset:384
	global_atomic_add_f32 v252, v246, s[90:91] offset:388
	s_or_b64 exec, exec, s[98:99]
	v_pk_mul_f32 v[158:159], v[158:159], s[16:17] op_sel_hi:[1,0]
	v_fma_f32 v166, -v158, v158, v159
	v_max_f32_e32 v166, 0, v166
	v_add_f32_e32 v166, 0x3727c5ac, v166
	v_rsq_f32_e32 v166, v166
	v_mov_b32_e32 v245, 0
	v_mov_b32_e32 v246, 0
	s_waitcnt vmcnt(23)
	v_lshlrev_b32_e32 v134, 16, v208
	v_and_b32_e32 v135, 0xffff0000, v208
	v_lshlrev_b32_e32 v136, 16, v209
	v_and_b32_e32 v137, 0xffff0000, v209
	v_pk_add_f32 v[134:135], v[134:135], v[158:159] op_sel_hi:[1,0] neg_lo:[0,1] neg_hi:[0,1]
	v_pk_add_f32 v[136:137], v[136:137], v[158:159] op_sel_hi:[1,0] neg_lo:[0,1] neg_hi:[0,1]
	v_pk_mul_f32 v[134:135], v[134:135], v[166:167] op_sel_hi:[1,0]
	v_pk_mul_f32 v[136:137], v[136:137], v[166:167] op_sel_hi:[1,0]
	v_pk_fma_f32 v[134:135], v[176:177], v[134:135], v[192:193]
	v_pk_fma_f32 v[136:137], v[178:179], v[136:137], v[194:195]
	v_pk_mul_f32 v[134:135], v[134:135], s[18:19] op_sel_hi:[1,0]
	v_pk_mul_f32 v[136:137], v[136:137], s[18:19] op_sel_hi:[1,0]
	v_pk_fma_f32 v[60:61], v[60:61], 0.5, v[134:135] op_sel_hi:[1,0,1]
	v_pk_fma_f32 v[62:63], v[62:63], 0.5, v[136:137] op_sel_hi:[1,0,1]
	v_add_f32_e32 v245, v245, v60
	v_fmac_f32_e32 v246, v60, v60
	v_add_f32_e32 v245, v245, v61
	v_fmac_f32_e32 v246, v61, v61
	v_add_f32_e32 v245, v245, v62
	v_fmac_f32_e32 v246, v62, v62
	v_add_f32_e32 v245, v245, v63
	v_fmac_f32_e32 v246, v63, v63
	s_waitcnt vmcnt(22)
	v_lshlrev_b32_e32 v240, 16, v210
	v_and_b32_e32 v241, 0xffff0000, v210
	v_lshlrev_b32_e32 v242, 16, v211
	v_and_b32_e32 v243, 0xffff0000, v211
	v_pk_add_f32 v[240:241], v[240:241], v[158:159] op_sel_hi:[1,0] neg_lo:[0,1] neg_hi:[0,1]
	v_pk_add_f32 v[242:243], v[242:243], v[158:159] op_sel_hi:[1,0] neg_lo:[0,1] neg_hi:[0,1]
	v_pk_mul_f32 v[240:241], v[240:241], v[166:167] op_sel_hi:[1,0]
	v_pk_mul_f32 v[242:243], v[242:243], v[166:167] op_sel_hi:[1,0]
	v_pk_fma_f32 v[240:241], v[180:181], v[240:241], v[196:197]
	v_pk_fma_f32 v[242:243], v[182:183], v[242:243], v[198:199]
	v_pk_mul_f32 v[240:241], v[240:241], s[18:19] op_sel_hi:[1,0]
	v_pk_mul_f32 v[242:243], v[242:243], s[18:19] op_sel_hi:[1,0]
	v_pk_fma_f32 v[56:57], v[56:57], 0.5, v[240:241] op_sel_hi:[1,0,1]
	v_pk_fma_f32 v[58:59], v[58:59], 0.5, v[242:243] op_sel_hi:[1,0,1]
	v_add_f32_e32 v245, v245, v56
	v_fmac_f32_e32 v246, v56, v56
	v_add_f32_e32 v245, v245, v57
	v_fmac_f32_e32 v246, v57, v57
	v_add_f32_e32 v245, v245, v58
	v_fmac_f32_e32 v246, v58, v58
	v_add_f32_e32 v245, v245, v59
	v_fmac_f32_e32 v246, v59, v59
	s_waitcnt vmcnt(21)
; template <int EPI>
; __device__ __forceinline__ void gemm_phase(const u16* __restrict__ A, const u16* __restrict__ Bt, const int K,
;                                            const int nN, char* shm, const EpiArgs& ea) {
;     ...
;                 for (int n = 0; n < 2; ++n) {
;                   const int col = cb + bj * 128 + n * 16;
;                   f32x4 c = acc[ai][bj][m][n];
;                   float h[4];
;                   if (EPI == EPI_FFN1) {
;                     float4 rv = *(const float4*)(ea.res + (size_t)row * DM + col);
;                     h[0] = rv.x; h[1] = rv.y; h[2] = rv.z; h[3] = rv.w;
;                   } else {
;                     uint2 yv = *(const uint2*)((const char*)ea.yb + tl_off(row, col, DM >> 6));
;                     float4 gv = *(const float4*)(ea.lng + col);
;                     float4 bv = *(const float4*)(ea.lnb + col);
;                     h[0] = (bf_lo(yv.x) - mu) * rstd * gv.x + bv.x; h[1] = (bf_hi(yv.x) - mu) * rstd * gv.y + bv.y;
;                     h[2] = (bf_lo(yv.y) - mu) * rstd * gv.z + bv.z; h[3] = (bf_hi(yv.y) - mu) * rstd * gv.w + bv.w;
;                   }
;                   float y[4];
;                   if (EPI == EPI_OUT) {
;                     float4 bo = *(const float4*)(ea.bias + col);
;                     y[0] = ALPHA * h[0] + c[0] + bo.x; y[1] = ALPHA * h[1] + c[1] + bo.y;
;                     y[2] = ALPHA * h[2] + c[2] + bo.z; y[3] = ALPHA * h[3] + c[3] + bo.w;
;                   } else {
; #pragma unroll
;                     for (int j = 0; j < 4; ++j) y[j] = ALPHA * h[j] + 0.5f * c[j];
;                   }
;                   if (EPI == EPI_FFN2) {
;                     *(float4*)(ea.outf + (size_t)row * DM + col) = make_float4(y[0], y[1], y[2], y[3]);
;                   } else {
;                     pk[n] = make_uint2(pack2(y[0], y[1]), pack2(y[2], y[3]));
;                     float q0 = bf_lo(pk[n].x), q1 = bf_hi(pk[n].x), q2 = bf_lo(pk[n].y), q3 = bf_hi(pk[n].y);
;                     rs += (q0 + q1) + (q2 + q3);
;                     rq += (q0 * q0 + q1 * q1) + (q2 * q2 + q3 * q3);
;                   }
;                 }
;                 if (EPI != EPI_FFN2) {
;                   const uint4 w = widen16(pk[0], pk[1]);
;                   *(uint4*)((char*)ea.yb + tl_off(row, cw + bj * 128, DM >> 6)) = w;
;                 }
;               }
	v_lshlrev_b32_e32 v134, 16, v212
	v_and_b32_e32 v135, 0xffff0000, v212
	v_lshlrev_b32_e32 v136, 16, v213
	v_and_b32_e32 v137, 0xffff0000, v213
	v_pk_add_f32 v[134:135], v[134:135], v[158:159] op_sel_hi:[1,0] neg_lo:[0,1] neg_hi:[0,1]
	v_pk_add_f32 v[136:137], v[136:137], v[158:159] op_sel_hi:[1,0] neg_lo:[0,1] neg_hi:[0,1]
	v_pk_mul_f32 v[134:135], v[134:135], v[166:167] op_sel_hi:[1,0]
	v_pk_mul_f32 v[136:137], v[136:137], v[166:167] op_sel_hi:[1,0]
	v_pk_fma_f32 v[134:135], v[184:185], v[134:135], v[200:201]
	v_pk_fma_f32 v[136:137], v[186:187], v[136:137], v[202:203]
	v_pk_mul_f32 v[134:135], v[134:135], s[18:19] op_sel_hi:[1,0]
	v_pk_mul_f32 v[136:137], v[136:137], s[18:19] op_sel_hi:[1,0]
	v_pk_fma_f32 v[52:53], v[52:53], 0.5, v[134:135] op_sel_hi:[1,0,1]
	v_pk_fma_f32 v[54:55], v[54:55], 0.5, v[136:137] op_sel_hi:[1,0,1]
	v_add_f32_e32 v245, v245, v52
	v_fmac_f32_e32 v246, v52, v52
	v_add_f32_e32 v245, v245, v53
	v_fmac_f32_e32 v246, v53, v53
	v_add_f32_e32 v245, v245, v54
	v_fmac_f32_e32 v246, v54, v54
	v_add_f32_e32 v245, v245, v55
	v_fmac_f32_e32 v246, v55, v55
	s_waitcnt vmcnt(20)
	v_lshlrev_b32_e32 v240, 16, v214
	v_and_b32_e32 v241, 0xffff0000, v214
	v_lshlrev_b32_e32 v242, 16, v215
	v_and_b32_e32 v243, 0xffff0000, v215
	v_pk_add_f32 v[240:241], v[240:241], v[158:159] op_sel_hi:[1,0] neg_lo:[0,1] neg_hi:[0,1]
	v_pk_add_f32 v[242:243], v[242:243], v[158:159] op_sel_hi:[1,0] neg_lo:[0,1] neg_hi:[0,1]
	v_pk_mul_f32 v[240:241], v[240:241], v[166:167] op_sel_hi:[1,0]
	v_pk_mul_f32 v[242:243], v[242:243], v[166:167] op_sel_hi:[1,0]
	v_pk_fma_f32 v[240:241], v[188:189], v[240:241], v[204:205]
	v_pk_fma_f32 v[242:243], v[190:191], v[242:243], v[206:207]
	v_pk_mul_f32 v[240:241], v[240:241], s[18:19] op_sel_hi:[1,0]
	v_pk_mul_f32 v[242:243], v[242:243], s[18:19] op_sel_hi:[1,0]
	v_pk_fma_f32 v[48:49], v[48:49], 0.5, v[240:241] op_sel_hi:[1,0,1]
	v_pk_fma_f32 v[50:51], v[50:51], 0.5, v[242:243] op_sel_hi:[1,0,1]
	v_add_f32_e32 v245, v245, v48
	v_fmac_f32_e32 v246, v48, v48
	v_add_f32_e32 v245, v245, v49
	v_fmac_f32_e32 v246, v49, v49
	v_add_f32_e32 v245, v245, v50
	v_fmac_f32_e32 v246, v50, v50
	v_add_f32_e32 v245, v245, v51
	v_fmac_f32_e32 v246, v51, v51
	v_mov_b32_e32 v247, v245
	v_mov_b32_e32 v248, v246
	s_nop 0
	v_permlane16_swap_b32_e32 v245, v247
	v_permlane16_swap_b32_e32 v246, v248
	v_add_f32_e32 v245, v245, v247
	v_add_f32_e32 v246, v246, v248
	v_mov_b32_e32 v247, v245
	v_mov_b32_e32 v248, v246
	s_nop 0
	v_permlane32_swap_b32_e32 v245, v247
	v_permlane32_swap_b32_e32 v246, v248
	v_add_f32_e32 v245, v245, v247
	v_add_f32_e32 v246, v246, v248
	v_and_b32_e32 v132, 48, v174
	v_cmp_eq_u32_e32 vcc, 0, v132
	s_and_saveexec_b64 s[98:99], vcc
	global_atomic_add_f32 v252, v245, s[90:91] offset:1024
	global_atomic_add_f32 v252, v246, s[90:91] offset:1028
	s_or_b64 exec, exec, s[98:99]
	v_pk_mul_f32 v[160:161], v[160:161], s[16:17] op_sel_hi:[1,0]
	v_fma_f32 v168, -v160, v160, v161
	v_max_f32_e32 v168, 0, v168
	v_add_f32_e32 v168, 0x3727c5ac, v168
	v_rsq_f32_e32 v168, v168
	v_mov_b32_e32 v245, 0
	v_mov_b32_e32 v246, 0
	s_waitcnt vmcnt(19)
	v_lshlrev_b32_e32 v134, 16, v216
	v_and_b32_e32 v135, 0xffff0000, v216
	v_lshlrev_b32_e32 v136, 16, v217
	v_and_b32_e32 v137, 0xffff0000, v217
	v_pk_add_f32 v[134:135], v[134:135], v[160:161] op_sel_hi:[1,0] neg_lo:[0,1] neg_hi:[0,1]
	v_pk_add_f32 v[136:137], v[136:137], v[160:161] op_sel_hi:[1,0] neg_lo:[0,1] neg_hi:[0,1]
	v_pk_mul_f32 v[134:135], v[134:135], v[168:169] op_sel_hi:[1,0]
	v_pk_mul_f32 v[136:137], v[136:137], v[168:169] op_sel_hi:[1,0]
	v_pk_fma_f32 v[134:135], v[176:177], v[134:135], v[192:193]
	v_pk_fma_f32 v[136:137], v[178:179], v[136:137], v[194:195]
	v_pk_mul_f32 v[134:135], v[134:135], s[18:19] op_sel_hi:[1,0]
	v_pk_mul_f32 v[136:137], v[136:137], s[18:19] op_sel_hi:[1,0]
	v_pk_fma_f32 v[44:45], v[44:45], 0.5, v[134:135] op_sel_hi:[1,0,1]
	v_pk_fma_f32 v[46:47], v[46:47], 0.5, v[136:137] op_sel_hi:[1,0,1]
	v_add_f32_e32 v245, v245, v44
	v_fmac_f32_e32 v246, v44, v44
	v_add_f32_e32 v245, v245, v45
	v_fmac_f32_e32 v246, v45, v45
	v_add_f32_e32 v245, v245, v46
	v_fmac_f32_e32 v246, v46, v46
	v_add_f32_e32 v245, v245, v47
	v_fmac_f32_e32 v246, v47, v47
	s_waitcnt vmcnt(18)
	v_lshlrev_b32_e32 v240, 16, v218
	v_and_b32_e32 v241, 0xffff0000, v218
	v_lshlrev_b32_e32 v242, 16, v219
	v_and_b32_e32 v243, 0xffff0000, v219
	v_pk_add_f32 v[240:241], v[240:241], v[160:161] op_sel_hi:[1,0] neg_lo:[0,1] neg_hi:[0,1]
	v_pk_add_f32 v[242:243], v[242:243], v[160:161] op_sel_hi:[1,0] neg_lo:[0,1] neg_hi:[0,1]
	v_pk_mul_f32 v[240:241], v[240:241], v[168:169] op_sel_hi:[1,0]
	v_pk_mul_f32 v[242:243], v[242:243], v[168:169] op_sel_hi:[1,0]
	v_pk_fma_f32 v[240:241], v[180:181], v[240:241], v[196:197]
	v_pk_fma_f32 v[242:243], v[182:183], v[242:243], v[198:199]
	v_pk_mul_f32 v[240:241], v[240:241], s[18:19] op_sel_hi:[1,0]
	v_pk_mul_f32 v[242:243], v[242:243], s[18:19] op_sel_hi:[1,0]
	v_pk_fma_f32 v[40:41], v[40:41], 0.5, v[240:241] op_sel_hi:[1,0,1]
	v_pk_fma_f32 v[42:43], v[42:43], 0.5, v[242:243] op_sel_hi:[1,0,1]
	v_add_f32_e32 v245, v245, v40
	v_fmac_f32_e32 v246, v40, v40
	v_add_f32_e32 v245, v245, v41
	v_fmac_f32_e32 v246, v41, v41
	v_add_f32_e32 v245, v245, v42
	v_fmac_f32_e32 v246, v42, v42
	v_add_f32_e32 v245, v245, v43
	v_fmac_f32_e32 v246, v43, v43
	s_waitcnt vmcnt(17)
; template <int EPI>
; __device__ __forceinline__ void gemm_phase(const u16* __restrict__ A, const u16* __restrict__ Bt, const int K,
;                                            const int nN, char* shm, const EpiArgs& ea) {
;     ...
;                 for (int n = 0; n < 2; ++n) {
;                   const int col = cb + bj * 128 + n * 16;
;                   f32x4 c = acc[ai][bj][m][n];
;                   float h[4];
;                   if (EPI == EPI_FFN1) {
;                     float4 rv = *(const float4*)(ea.res + (size_t)row * DM + col);
;                     h[0] = rv.x; h[1] = rv.y; h[2] = rv.z; h[3] = rv.w;
;                   } else {
;                     uint2 yv = *(const uint2*)((const char*)ea.yb + tl_off(row, col, DM >> 6));
;                     float4 gv = *(const float4*)(ea.lng + col);
;                     float4 bv = *(const float4*)(ea.lnb + col);
;                     h[0] = (bf_lo(yv.x) - mu) * rstd * gv.x + bv.x; h[1] = (bf_hi(yv.x) - mu) * rstd * gv.y + bv.y;
;                     h[2] = (bf_lo(yv.y) - mu) * rstd * gv.z + bv.z; h[3] = (bf_hi(yv.y) - mu) * rstd * gv.w + bv.w;
;                   }
;                   float y[4];
;                   if (EPI == EPI_OUT) {
;                     float4 bo = *(const float4*)(ea.bias + col);
;                     y[0] = ALPHA * h[0] + c[0] + bo.x; y[1] = ALPHA * h[1] + c[1] + bo.y;
;                     y[2] = ALPHA * h[2] + c[2] + bo.z; y[3] = ALPHA * h[3] + c[3] + bo.w;
;                   } else {
; #pragma unroll
;                     for (int j = 0; j < 4; ++j) y[j] = ALPHA * h[j] + 0.5f * c[j];
;                   }
;                   if (EPI == EPI_FFN2) {
;                     *(float4*)(ea.outf + (size_t)row * DM + col) = make_float4(y[0], y[1], y[2], y[3]);
;                   } else {
;                     pk[n] = make_uint2(pack2(y[0], y[1]), pack2(y[2], y[3]));
;                     float q0 = bf_lo(pk[n].x), q1 = bf_hi(pk[n].x), q2 = bf_lo(pk[n].y), q3 = bf_hi(pk[n].y);
;                     rs += (q0 + q1) + (q2 + q3);
;                     rq += (q0 * q0 + q1 * q1) + (q2 * q2 + q3 * q3);
;                   }
;                 }
;                 if (EPI != EPI_FFN2) {
;                   const uint4 w = widen16(pk[0], pk[1]);
;                   *(uint4*)((char*)ea.yb + tl_off(row, cw + bj * 128, DM >> 6)) = w;
;                 }
;               }
	v_lshlrev_b32_e32 v134, 16, v220
	v_and_b32_e32 v135, 0xffff0000, v220
	v_lshlrev_b32_e32 v136, 16, v221
	v_and_b32_e32 v137, 0xffff0000, v221
	v_pk_add_f32 v[134:135], v[134:135], v[160:161] op_sel_hi:[1,0] neg_lo:[0,1] neg_hi:[0,1]
	v_pk_add_f32 v[136:137], v[136:137], v[160:161] op_sel_hi:[1,0] neg_lo:[0,1] neg_hi:[0,1]
	v_pk_mul_f32 v[134:135], v[134:135], v[168:169] op_sel_hi:[1,0]
	v_pk_mul_f32 v[136:137], v[136:137], v[168:169] op_sel_hi:[1,0]
	v_pk_fma_f32 v[134:135], v[184:185], v[134:135], v[200:201]
	v_pk_fma_f32 v[136:137], v[186:187], v[136:137], v[202:203]
	v_pk_mul_f32 v[134:135], v[134:135], s[18:19] op_sel_hi:[1,0]
	v_pk_mul_f32 v[136:137], v[136:137], s[18:19] op_sel_hi:[1,0]
	v_pk_fma_f32 v[36:37], v[36:37], 0.5, v[134:135] op_sel_hi:[1,0,1]
	v_pk_fma_f32 v[38:39], v[38:39], 0.5, v[136:137] op_sel_hi:[1,0,1]
	v_add_f32_e32 v245, v245, v36
	v_fmac_f32_e32 v246, v36, v36
	v_add_f32_e32 v245, v245, v37
	v_fmac_f32_e32 v246, v37, v37
	v_add_f32_e32 v245, v245, v38
	v_fmac_f32_e32 v246, v38, v38
	v_add_f32_e32 v245, v245, v39
	v_fmac_f32_e32 v246, v39, v39
	s_waitcnt vmcnt(16)
	v_lshlrev_b32_e32 v240, 16, v222
	v_and_b32_e32 v241, 0xffff0000, v222
	v_lshlrev_b32_e32 v242, 16, v223
	v_and_b32_e32 v243, 0xffff0000, v223
	v_pk_add_f32 v[240:241], v[240:241], v[160:161] op_sel_hi:[1,0] neg_lo:[0,1] neg_hi:[0,1]
	v_pk_add_f32 v[242:243], v[242:243], v[160:161] op_sel_hi:[1,0] neg_lo:[0,1] neg_hi:[0,1]
	v_pk_mul_f32 v[240:241], v[240:241], v[168:169] op_sel_hi:[1,0]
	v_pk_mul_f32 v[242:243], v[242:243], v[168:169] op_sel_hi:[1,0]
	v_pk_fma_f32 v[240:241], v[188:189], v[240:241], v[204:205]
	v_pk_fma_f32 v[242:243], v[190:191], v[242:243], v[206:207]
	v_pk_mul_f32 v[240:241], v[240:241], s[18:19] op_sel_hi:[1,0]
	v_pk_mul_f32 v[242:243], v[242:243], s[18:19] op_sel_hi:[1,0]
	v_pk_fma_f32 v[32:33], v[32:33], 0.5, v[240:241] op_sel_hi:[1,0,1]
	v_pk_fma_f32 v[34:35], v[34:35], 0.5, v[242:243] op_sel_hi:[1,0,1]
	v_add_f32_e32 v245, v245, v32
	v_fmac_f32_e32 v246, v32, v32
	v_add_f32_e32 v245, v245, v33
	v_fmac_f32_e32 v246, v33, v33
	v_add_f32_e32 v245, v245, v34
	v_fmac_f32_e32 v246, v34, v34
	v_add_f32_e32 v245, v245, v35
	v_fmac_f32_e32 v246, v35, v35
	v_mov_b32_e32 v247, v245
	v_mov_b32_e32 v248, v246
	s_nop 0
	v_permlane16_swap_b32_e32 v245, v247
	v_permlane16_swap_b32_e32 v246, v248
	v_add_f32_e32 v245, v245, v247
	v_add_f32_e32 v246, v246, v248
	v_mov_b32_e32 v247, v245
	v_mov_b32_e32 v248, v246
	s_nop 0
	v_permlane32_swap_b32_e32 v245, v247
	v_permlane32_swap_b32_e32 v246, v248
	v_add_f32_e32 v245, v245, v247
	v_add_f32_e32 v246, v246, v248
	v_and_b32_e32 v132, 48, v174
	v_cmp_eq_u32_e32 vcc, 0, v132
	s_and_saveexec_b64 s[98:99], vcc
	global_atomic_add_f32 v252, v245, s[90:91] offset:1152
	global_atomic_add_f32 v252, v246, s[90:91] offset:1156
	s_or_b64 exec, exec, s[98:99]
	v_pk_mul_f32 v[162:163], v[162:163], s[16:17] op_sel_hi:[1,0]
	v_fma_f32 v166, -v162, v162, v163
	v_max_f32_e32 v166, 0, v166
	v_add_f32_e32 v166, 0x3727c5ac, v166
	v_rsq_f32_e32 v166, v166
	v_mov_b32_e32 v245, 0
	v_mov_b32_e32 v246, 0
	s_waitcnt vmcnt(15)
	v_lshlrev_b32_e32 v134, 16, v224
	v_and_b32_e32 v135, 0xffff0000, v224
	v_lshlrev_b32_e32 v136, 16, v225
	v_and_b32_e32 v137, 0xffff0000, v225
	v_pk_add_f32 v[134:135], v[134:135], v[162:163] op_sel_hi:[1,0] neg_lo:[0,1] neg_hi:[0,1]
	v_pk_add_f32 v[136:137], v[136:137], v[162:163] op_sel_hi:[1,0] neg_lo:[0,1] neg_hi:[0,1]
	v_pk_mul_f32 v[134:135], v[134:135], v[166:167] op_sel_hi:[1,0]
	v_pk_mul_f32 v[136:137], v[136:137], v[166:167] op_sel_hi:[1,0]
	v_pk_fma_f32 v[134:135], v[176:177], v[134:135], v[192:193]
	v_pk_fma_f32 v[136:137], v[178:179], v[136:137], v[194:195]
	v_pk_mul_f32 v[134:135], v[134:135], s[18:19] op_sel_hi:[1,0]
	v_pk_mul_f32 v[136:137], v[136:137], s[18:19] op_sel_hi:[1,0]
	v_pk_fma_f32 v[28:29], v[28:29], 0.5, v[134:135] op_sel_hi:[1,0,1]
	v_pk_fma_f32 v[30:31], v[30:31], 0.5, v[136:137] op_sel_hi:[1,0,1]
	v_add_f32_e32 v245, v245, v28
	v_fmac_f32_e32 v246, v28, v28
	v_add_f32_e32 v245, v245, v29
	v_fmac_f32_e32 v246, v29, v29
	v_add_f32_e32 v245, v245, v30
	v_fmac_f32_e32 v246, v30, v30
	v_add_f32_e32 v245, v245, v31
	v_fmac_f32_e32 v246, v31, v31
	s_waitcnt vmcnt(14)
	v_lshlrev_b32_e32 v240, 16, v226
	v_and_b32_e32 v241, 0xffff0000, v226
	v_lshlrev_b32_e32 v242, 16, v227
	v_and_b32_e32 v243, 0xffff0000, v227
	v_pk_add_f32 v[240:241], v[240:241], v[162:163] op_sel_hi:[1,0] neg_lo:[0,1] neg_hi:[0,1]
	v_pk_add_f32 v[242:243], v[242:243], v[162:163] op_sel_hi:[1,0] neg_lo:[0,1] neg_hi:[0,1]
	v_pk_mul_f32 v[240:241], v[240:241], v[166:167] op_sel_hi:[1,0]
	v_pk_mul_f32 v[242:243], v[242:243], v[166:167] op_sel_hi:[1,0]
	v_pk_fma_f32 v[240:241], v[180:181], v[240:241], v[196:197]
	v_pk_fma_f32 v[242:243], v[182:183], v[242:243], v[198:199]
	v_pk_mul_f32 v[240:241], v[240:241], s[18:19] op_sel_hi:[1,0]
	v_pk_mul_f32 v[242:243], v[242:243], s[18:19] op_sel_hi:[1,0]
	v_pk_fma_f32 v[24:25], v[24:25], 0.5, v[240:241] op_sel_hi:[1,0,1]
	v_pk_fma_f32 v[26:27], v[26:27], 0.5, v[242:243] op_sel_hi:[1,0,1]
	v_add_f32_e32 v245, v245, v24
	v_fmac_f32_e32 v246, v24, v24
	v_add_f32_e32 v245, v245, v25
	v_fmac_f32_e32 v246, v25, v25
	v_add_f32_e32 v245, v245, v26
	v_fmac_f32_e32 v246, v26, v26
	v_add_f32_e32 v245, v245, v27
	v_fmac_f32_e32 v246, v27, v27
	s_waitcnt vmcnt(13)
; template <int EPI>
; __device__ __forceinline__ void gemm_phase(const u16* __restrict__ A, const u16* __restrict__ Bt, const int K,
;                                            const int nN, char* shm, const EpiArgs& ea) {
;     ...
;                 for (int n = 0; n < 2; ++n) {
;                   const int col = cb + bj * 128 + n * 16;
;                   f32x4 c = acc[ai][bj][m][n];
;                   float h[4];
;                   if (EPI == EPI_FFN1) {
;                     float4 rv = *(const float4*)(ea.res + (size_t)row * DM + col);
;                     h[0] = rv.x; h[1] = rv.y; h[2] = rv.z; h[3] = rv.w;
;                   } else {
;                     uint2 yv = *(const uint2*)((const char*)ea.yb + tl_off(row, col, DM >> 6));
;                     float4 gv = *(const float4*)(ea.lng + col);
;                     float4 bv = *(const float4*)(ea.lnb + col);
;                     h[0] = (bf_lo(yv.x) - mu) * rstd * gv.x + bv.x; h[1] = (bf_hi(yv.x) - mu) * rstd * gv.y + bv.y;
;                     h[2] = (bf_lo(yv.y) - mu) * rstd * gv.z + bv.z; h[3] = (bf_hi(yv.y) - mu) * rstd * gv.w + bv.w;
;                   }
;                   float y[4];
;                   if (EPI == EPI_OUT) {
;                     float4 bo = *(const float4*)(ea.bias + col);
;                     y[0] = ALPHA * h[0] + c[0] + bo.x; y[1] = ALPHA * h[1] + c[1] + bo.y;
;                     y[2] = ALPHA * h[2] + c[2] + bo.z; y[3] = ALPHA * h[3] + c[3] + bo.w;
;                   } else {
; #pragma unroll
;                     for (int j = 0; j < 4; ++j) y[j] = ALPHA * h[j] + 0.5f * c[j];
;                   }
;                   if (EPI == EPI_FFN2) {
;                     *(float4*)(ea.outf + (size_t)row * DM + col) = make_float4(y[0], y[1], y[2], y[3]);
;                   } else {
;                     pk[n] = make_uint2(pack2(y[0], y[1]), pack2(y[2], y[3]));
;                     float q0 = bf_lo(pk[n].x), q1 = bf_hi(pk[n].x), q2 = bf_lo(pk[n].y), q3 = bf_hi(pk[n].y);
;                     rs += (q0 + q1) + (q2 + q3);
;                     rq += (q0 * q0 + q1 * q1) + (q2 * q2 + q3 * q3);
;                   }
;                 }
;                 if (EPI != EPI_FFN2) {
;                   const uint4 w = widen16(pk[0], pk[1]);
;                   *(uint4*)((char*)ea.yb + tl_off(row, cw + bj * 128, DM >> 6)) = w;
;                 }
;               }
	v_lshlrev_b32_e32 v134, 16, v228
	v_and_b32_e32 v135, 0xffff0000, v228
	v_lshlrev_b32_e32 v136, 16, v229
	v_and_b32_e32 v137, 0xffff0000, v229
	v_pk_add_f32 v[134:135], v[134:135], v[162:163] op_sel_hi:[1,0] neg_lo:[0,1] neg_hi:[0,1]
	v_pk_add_f32 v[136:137], v[136:137], v[162:163] op_sel_hi:[1,0] neg_lo:[0,1] neg_hi:[0,1]
	v_pk_mul_f32 v[134:135], v[134:135], v[166:167] op_sel_hi:[1,0]
	v_pk_mul_f32 v[136:137], v[136:137], v[166:167] op_sel_hi:[1,0]
	v_pk_fma_f32 v[134:135], v[184:185], v[134:135], v[200:201]
	v_pk_fma_f32 v[136:137], v[186:187], v[136:137], v[202:203]
	v_pk_mul_f32 v[134:135], v[134:135], s[18:19] op_sel_hi:[1,0]
	v_pk_mul_f32 v[136:137], v[136:137], s[18:19] op_sel_hi:[1,0]
	v_pk_fma_f32 v[20:21], v[20:21], 0.5, v[134:135] op_sel_hi:[1,0,1]
	v_pk_fma_f32 v[22:23], v[22:23], 0.5, v[136:137] op_sel_hi:[1,0,1]
	v_add_f32_e32 v245, v245, v20
	v_fmac_f32_e32 v246, v20, v20
	v_add_f32_e32 v245, v245, v21
	v_fmac_f32_e32 v246, v21, v21
	v_add_f32_e32 v245, v245, v22
	v_fmac_f32_e32 v246, v22, v22
	v_add_f32_e32 v245, v245, v23
	v_fmac_f32_e32 v246, v23, v23
	s_waitcnt vmcnt(12)
	v_lshlrev_b32_e32 v240, 16, v230
	v_and_b32_e32 v241, 0xffff0000, v230
	v_lshlrev_b32_e32 v242, 16, v231
	v_and_b32_e32 v243, 0xffff0000, v231
	v_pk_add_f32 v[240:241], v[240:241], v[162:163] op_sel_hi:[1,0] neg_lo:[0,1] neg_hi:[0,1]
	v_pk_add_f32 v[242:243], v[242:243], v[162:163] op_sel_hi:[1,0] neg_lo:[0,1] neg_hi:[0,1]
	v_pk_mul_f32 v[240:241], v[240:241], v[166:167] op_sel_hi:[1,0]
	v_pk_mul_f32 v[242:243], v[242:243], v[166:167] op_sel_hi:[1,0]
	v_pk_fma_f32 v[240:241], v[188:189], v[240:241], v[204:205]
	v_pk_fma_f32 v[242:243], v[190:191], v[242:243], v[206:207]
	v_pk_mul_f32 v[240:241], v[240:241], s[18:19] op_sel_hi:[1,0]
	v_pk_mul_f32 v[242:243], v[242:243], s[18:19] op_sel_hi:[1,0]
	v_pk_fma_f32 v[16:17], v[16:17], 0.5, v[240:241] op_sel_hi:[1,0,1]
	v_pk_fma_f32 v[18:19], v[18:19], 0.5, v[242:243] op_sel_hi:[1,0,1]
	v_add_f32_e32 v245, v245, v16
	v_fmac_f32_e32 v246, v16, v16
	v_add_f32_e32 v245, v245, v17
	v_fmac_f32_e32 v246, v17, v17
	v_add_f32_e32 v245, v245, v18
	v_fmac_f32_e32 v246, v18, v18
	v_add_f32_e32 v245, v245, v19
	v_fmac_f32_e32 v246, v19, v19
	v_mov_b32_e32 v247, v245
	v_mov_b32_e32 v248, v246
	s_nop 0
	v_permlane16_swap_b32_e32 v245, v247
	v_permlane16_swap_b32_e32 v246, v248
	v_add_f32_e32 v245, v245, v247
	v_add_f32_e32 v246, v246, v248
	v_mov_b32_e32 v247, v245
	v_mov_b32_e32 v248, v246
	s_nop 0
	v_permlane32_swap_b32_e32 v245, v247
	v_permlane32_swap_b32_e32 v246, v248
	v_add_f32_e32 v245, v245, v247
	v_add_f32_e32 v246, v246, v248
	v_and_b32_e32 v132, 48, v174
	v_cmp_eq_u32_e32 vcc, 0, v132
	s_and_saveexec_b64 s[98:99], vcc
	global_atomic_add_f32 v252, v245, s[90:91] offset:1280
	global_atomic_add_f32 v252, v246, s[90:91] offset:1284
	s_or_b64 exec, exec, s[98:99]
	v_pk_mul_f32 v[164:165], v[164:165], s[16:17] op_sel_hi:[1,0]
	v_fma_f32 v168, -v164, v164, v165
	v_max_f32_e32 v168, 0, v168
	v_add_f32_e32 v168, 0x3727c5ac, v168
	v_rsq_f32_e32 v168, v168
	v_mov_b32_e32 v245, 0
	v_mov_b32_e32 v246, 0
	s_waitcnt vmcnt(11)
	v_lshlrev_b32_e32 v134, 16, v232
	v_and_b32_e32 v135, 0xffff0000, v232
	v_lshlrev_b32_e32 v136, 16, v233
	v_and_b32_e32 v137, 0xffff0000, v233
	v_pk_add_f32 v[134:135], v[134:135], v[164:165] op_sel_hi:[1,0] neg_lo:[0,1] neg_hi:[0,1]
	v_pk_add_f32 v[136:137], v[136:137], v[164:165] op_sel_hi:[1,0] neg_lo:[0,1] neg_hi:[0,1]
	v_pk_mul_f32 v[134:135], v[134:135], v[168:169] op_sel_hi:[1,0]
	v_pk_mul_f32 v[136:137], v[136:137], v[168:169] op_sel_hi:[1,0]
	v_pk_fma_f32 v[134:135], v[176:177], v[134:135], v[192:193]
	v_pk_fma_f32 v[136:137], v[178:179], v[136:137], v[194:195]
	v_pk_mul_f32 v[134:135], v[134:135], s[18:19] op_sel_hi:[1,0]
	v_pk_mul_f32 v[136:137], v[136:137], s[18:19] op_sel_hi:[1,0]
	v_pk_fma_f32 v[12:13], v[12:13], 0.5, v[134:135] op_sel_hi:[1,0,1]
	v_pk_fma_f32 v[14:15], v[14:15], 0.5, v[136:137] op_sel_hi:[1,0,1]
	v_add_f32_e32 v245, v245, v12
	v_fmac_f32_e32 v246, v12, v12
	v_add_f32_e32 v245, v245, v13
	v_fmac_f32_e32 v246, v13, v13
	v_add_f32_e32 v245, v245, v14
	v_fmac_f32_e32 v246, v14, v14
	v_add_f32_e32 v245, v245, v15
	v_fmac_f32_e32 v246, v15, v15
	s_waitcnt vmcnt(10)
	v_lshlrev_b32_e32 v240, 16, v234
	v_and_b32_e32 v241, 0xffff0000, v234
	v_lshlrev_b32_e32 v242, 16, v235
	v_and_b32_e32 v243, 0xffff0000, v235
	v_pk_add_f32 v[240:241], v[240:241], v[164:165] op_sel_hi:[1,0] neg_lo:[0,1] neg_hi:[0,1]
	v_pk_add_f32 v[242:243], v[242:243], v[164:165] op_sel_hi:[1,0] neg_lo:[0,1] neg_hi:[0,1]
	v_pk_mul_f32 v[240:241], v[240:241], v[168:169] op_sel_hi:[1,0]
	v_pk_mul_f32 v[242:243], v[242:243], v[168:169] op_sel_hi:[1,0]
	v_pk_fma_f32 v[240:241], v[180:181], v[240:241], v[196:197]
	v_pk_fma_f32 v[242:243], v[182:183], v[242:243], v[198:199]
	v_pk_mul_f32 v[240:241], v[240:241], s[18:19] op_sel_hi:[1,0]
	v_pk_mul_f32 v[242:243], v[242:243], s[18:19] op_sel_hi:[1,0]
	v_pk_fma_f32 v[8:9], v[8:9], 0.5, v[240:241] op_sel_hi:[1,0,1]
	v_pk_fma_f32 v[10:11], v[10:11], 0.5, v[242:243] op_sel_hi:[1,0,1]
	v_add_f32_e32 v245, v245, v8
	v_fmac_f32_e32 v246, v8, v8
	v_add_f32_e32 v245, v245, v9
	v_fmac_f32_e32 v246, v9, v9
	v_add_f32_e32 v245, v245, v10
	v_fmac_f32_e32 v246, v10, v10
	v_add_f32_e32 v245, v245, v11
	v_fmac_f32_e32 v246, v11, v11
	s_waitcnt vmcnt(9)
; template <int EPI>
; __device__ __forceinline__ void gemm_phase(const u16* __restrict__ A, const u16* __restrict__ Bt, const int K,
;                                            const int nN, char* shm, const EpiArgs& ea) {
;     ...
;                 for (int n = 0; n < 2; ++n) {
;                   const int col = cb + bj * 128 + n * 16;
;                   f32x4 c = acc[ai][bj][m][n];
;                   float h[4];
;                   if (EPI == EPI_FFN1) {
;                     float4 rv = *(const float4*)(ea.res + (size_t)row * DM + col);
;                     h[0] = rv.x; h[1] = rv.y; h[2] = rv.z; h[3] = rv.w;
;                   } else {
;                     uint2 yv = *(const uint2*)((const char*)ea.yb + tl_off(row, col, DM >> 6));
;                     float4 gv = *(const float4*)(ea.lng + col);
;                     float4 bv = *(const float4*)(ea.lnb + col);
;                     h[0] = (bf_lo(yv.x) - mu) * rstd * gv.x + bv.x; h[1] = (bf_hi(yv.x) - mu) * rstd * gv.y + bv.y;
;                     h[2] = (bf_lo(yv.y) - mu) * rstd * gv.z + bv.z; h[3] = (bf_hi(yv.y) - mu) * rstd * gv.w + bv.w;
;                   }
;                   float y[4];
;                   if (EPI == EPI_OUT) {
;                     float4 bo = *(const float4*)(ea.bias + col);
;                     y[0] = ALPHA * h[0] + c[0] + bo.x; y[1] = ALPHA * h[1] + c[1] + bo.y;
;                     y[2] = ALPHA * h[2] + c[2] + bo.z; y[3] = ALPHA * h[3] + c[3] + bo.w;
;                   } else {
; #pragma unroll
;                     for (int j = 0; j < 4; ++j) y[j] = ALPHA * h[j] + 0.5f * c[j];
;                   }
;                   if (EPI == EPI_FFN2) {
;                     *(float4*)(ea.outf + (size_t)row * DM + col) = make_float4(y[0], y[1], y[2], y[3]);
;                   } else {
;                     pk[n] = make_uint2(pack2(y[0], y[1]), pack2(y[2], y[3]));
;                     float q0 = bf_lo(pk[n].x), q1 = bf_hi(pk[n].x), q2 = bf_lo(pk[n].y), q3 = bf_hi(pk[n].y);
;                     rs += (q0 + q1) + (q2 + q3);
;                     rq += (q0 * q0 + q1 * q1) + (q2 * q2 + q3 * q3);
;                   }
;                 }
;                 if (EPI != EPI_FFN2) {
;                   const uint4 w = widen16(pk[0], pk[1]);
;                   *(uint4*)((char*)ea.yb + tl_off(row, cw + bj * 128, DM >> 6)) = w;
;                 }
;               }
	v_lshlrev_b32_e32 v134, 16, v236
	v_and_b32_e32 v135, 0xffff0000, v236
	v_lshlrev_b32_e32 v136, 16, v237
	v_and_b32_e32 v137, 0xffff0000, v237
	v_pk_add_f32 v[134:135], v[134:135], v[164:165] op_sel_hi:[1,0] neg_lo:[0,1] neg_hi:[0,1]
	v_pk_add_f32 v[136:137], v[136:137], v[164:165] op_sel_hi:[1,0] neg_lo:[0,1] neg_hi:[0,1]
	v_pk_mul_f32 v[134:135], v[134:135], v[168:169] op_sel_hi:[1,0]
	v_pk_mul_f32 v[136:137], v[136:137], v[168:169] op_sel_hi:[1,0]
	v_pk_fma_f32 v[134:135], v[184:185], v[134:135], v[200:201]
	v_pk_fma_f32 v[136:137], v[186:187], v[136:137], v[202:203]
	v_pk_mul_f32 v[134:135], v[134:135], s[18:19] op_sel_hi:[1,0]
	v_pk_mul_f32 v[136:137], v[136:137], s[18:19] op_sel_hi:[1,0]
	v_pk_fma_f32 v[4:5], v[4:5], 0.5, v[134:135] op_sel_hi:[1,0,1]
	v_pk_fma_f32 v[6:7], v[6:7], 0.5, v[136:137] op_sel_hi:[1,0,1]
	v_add_f32_e32 v245, v245, v4
	v_fmac_f32_e32 v246, v4, v4
	v_add_f32_e32 v245, v245, v5
	v_fmac_f32_e32 v246, v5, v5
	v_add_f32_e32 v245, v245, v6
	v_fmac_f32_e32 v246, v6, v6
	v_add_f32_e32 v245, v245, v7
	v_fmac_f32_e32 v246, v7, v7
	s_waitcnt vmcnt(8)
	v_lshlrev_b32_e32 v240, 16, v238
	v_and_b32_e32 v241, 0xffff0000, v238
	v_lshlrev_b32_e32 v242, 16, v239
	v_and_b32_e32 v243, 0xffff0000, v239
	v_pk_add_f32 v[240:241], v[240:241], v[164:165] op_sel_hi:[1,0] neg_lo:[0,1] neg_hi:[0,1]
	v_pk_add_f32 v[242:243], v[242:243], v[164:165] op_sel_hi:[1,0] neg_lo:[0,1] neg_hi:[0,1]
	v_pk_mul_f32 v[240:241], v[240:241], v[168:169] op_sel_hi:[1,0]
	v_pk_mul_f32 v[242:243], v[242:243], v[168:169] op_sel_hi:[1,0]
	v_pk_fma_f32 v[240:241], v[188:189], v[240:241], v[204:205]
	v_pk_fma_f32 v[242:243], v[190:191], v[242:243], v[206:207]
	v_pk_mul_f32 v[240:241], v[240:241], s[18:19] op_sel_hi:[1,0]
	v_pk_mul_f32 v[242:243], v[242:243], s[18:19] op_sel_hi:[1,0]
	v_pk_fma_f32 v[0:1], v[0:1], 0.5, v[240:241] op_sel_hi:[1,0,1]
	v_pk_fma_f32 v[2:3], v[2:3], 0.5, v[242:243] op_sel_hi:[1,0,1]
	v_add_f32_e32 v245, v245, v0
	v_fmac_f32_e32 v246, v0, v0
	v_add_f32_e32 v245, v245, v1
	v_fmac_f32_e32 v246, v1, v1
	v_add_f32_e32 v245, v245, v2
	v_fmac_f32_e32 v246, v2, v2
	v_add_f32_e32 v245, v245, v3
	v_fmac_f32_e32 v246, v3, v3
	v_mov_b32_e32 v247, v245
	v_mov_b32_e32 v248, v246
	s_nop 0
	v_permlane16_swap_b32_e32 v245, v247
	v_permlane16_swap_b32_e32 v246, v248
	v_add_f32_e32 v245, v245, v247
	v_add_f32_e32 v246, v246, v248
	v_mov_b32_e32 v247, v245
	v_mov_b32_e32 v248, v246
	s_nop 0
	v_permlane32_swap_b32_e32 v245, v247
	v_permlane32_swap_b32_e32 v246, v248
	v_add_f32_e32 v245, v245, v247
	v_add_f32_e32 v246, v246, v248
	v_and_b32_e32 v132, 48, v174
	v_cmp_eq_u32_e32 vcc, 0, v132
	s_and_saveexec_b64 s[98:99], vcc
	global_atomic_add_f32 v252, v245, s[90:91] offset:1408
	global_atomic_add_f32 v252, v246, s[90:91] offset:1412
	s_or_b64 exec, exec, s[98:99]
	global_load_dwordx4 v[176:179], v173, s[84:85]
	global_load_dwordx4 v[192:195], v173, s[86:87]
	global_load_dwordx4 v[180:183], v173, s[84:85] offset:64
	global_load_dwordx4 v[196:199], v173, s[86:87] offset:64
	global_load_dwordx4 v[184:187], v173, s[84:85] offset:512
	global_load_dwordx4 v[200:203], v173, s[86:87] offset:512
	global_load_dwordx4 v[188:191], v173, s[84:85] offset:576
	global_load_dwordx4 v[204:207], v173, s[86:87] offset:576
	s_waitcnt vmcnt(0)
	s_barrier
	v_readfirstlane_b32 s98, v174
	s_nop 3
	s_cmp_lt_u32 s98, 64
	s_cbranch_scc0 .Lp7_sync_done
	s_mov_b64 exec, 1
	v_mov_b32_e32 v249, s100
	v_mov_b32_e32 v250, 1
	s_mov_b32 s99, 0
	buffer_wbl2 sc1
	s_waitcnt vmcnt(0)
	global_atomic_add v249, v250, s[90:91]
.Lp7_spin:
	s_sleep 1
	global_load_dword v251, v249, s[90:91] sc1
	s_add_i32 s99, s99, 1
	s_waitcnt vmcnt(0)
	v_readfirstlane_b32 s98, v251
	s_nop 3
	s_cmp_ge_u32 s98, 8
	s_cbranch_scc1 .Lp7_spin_end
	s_cmp_lt_u32 s99, 0x80000
	s_cbranch_scc1 .Lp7_spin
.Lp7_spin_end:
	buffer_inv sc1
	s_mov_b64 exec, -1
.Lp7_sync_done:
	s_barrier
	global_load_dwordx2 v[150:151], v252, s[90:91] sc1
	global_load_dwordx2 v[152:153], v252, s[90:91] offset:128 sc1
	global_load_dwordx2 v[154:155], v252, s[90:91] offset:256 sc1
	global_load_dwordx2 v[156:157], v252, s[90:91] offset:384 sc1
	global_load_dwordx2 v[158:159], v252, s[90:91] offset:1024 sc1
	global_load_dwordx2 v[160:161], v252, s[90:91] offset:1152 sc1
	global_load_dwordx2 v[162:163], v252, s[90:91] offset:1280 sc1
	global_load_dwordx2 v[164:165], v252, s[90:91] offset:1408 sc1
	s_waitcnt vmcnt(7)
	v_pk_mul_f32 v[150:151], v[150:151], s[16:17] op_sel_hi:[1,0]
	v_mov_b32_e32 v133, v128
	v_fma_f32 v166, -v150, v150, v151
	v_max_f32_e32 v166, 0, v166
	v_add_f32_e32 v166, 0x3727c5ac, v166
	v_rsq_f32_e32 v166, v166
	s_nop 0
	v_pk_add_f32 v[124:125], v[124:125], v[150:151] op_sel_hi:[1,0] neg_lo:[0,1] neg_hi:[0,1]
	v_pk_add_f32 v[126:127], v[126:127], v[150:151] op_sel_hi:[1,0] neg_lo:[0,1] neg_hi:[0,1]
	v_pk_mul_f32 v[124:125], v[124:125], v[166:167] op_sel_hi:[1,0]
	v_pk_mul_f32 v[126:127], v[126:127], v[166:167] op_sel_hi:[1,0]
	v_pk_fma_f32 v[124:125], v[176:177], v[124:125], v[192:193]
	v_pk_fma_f32 v[126:127], v[178:179], v[126:127], v[194:195]
	global_store_dwordx4 v133, v[124:127], s[88:89]
	v_pk_add_f32 v[120:121], v[120:121], v[150:151] op_sel_hi:[1,0] neg_lo:[0,1] neg_hi:[0,1]
	v_pk_add_f32 v[122:123], v[122:123], v[150:151] op_sel_hi:[1,0] neg_lo:[0,1] neg_hi:[0,1]
	v_pk_mul_f32 v[120:121], v[120:121], v[166:167] op_sel_hi:[1,0]
	v_pk_mul_f32 v[122:123], v[122:123], v[166:167] op_sel_hi:[1,0]
	v_pk_fma_f32 v[120:121], v[180:181], v[120:121], v[196:197]
	v_pk_fma_f32 v[122:123], v[182:183], v[122:123], v[198:199]
	global_store_dwordx4 v133, v[120:123], s[88:89] offset:64
	v_pk_add_f32 v[116:117], v[116:117], v[150:151] op_sel_hi:[1,0] neg_lo:[0,1] neg_hi:[0,1]
	v_pk_add_f32 v[118:119], v[118:119], v[150:151] op_sel_hi:[1,0] neg_lo:[0,1] neg_hi:[0,1]
	v_pk_mul_f32 v[116:117], v[116:117], v[166:167] op_sel_hi:[1,0]
	v_pk_mul_f32 v[118:119], v[118:119], v[166:167] op_sel_hi:[1,0]
	v_pk_fma_f32 v[116:117], v[184:185], v[116:117], v[200:201]
	v_pk_fma_f32 v[118:119], v[186:187], v[118:119], v[202:203]
	global_store_dwordx4 v133, v[116:119], s[88:89] offset:512
	v_pk_add_f32 v[112:113], v[112:113], v[150:151] op_sel_hi:[1,0] neg_lo:[0,1] neg_hi:[0,1]
	v_pk_add_f32 v[114:115], v[114:115], v[150:151] op_sel_hi:[1,0] neg_lo:[0,1] neg_hi:[0,1]
	v_pk_mul_f32 v[112:113], v[112:113], v[166:167] op_sel_hi:[1,0]
	v_pk_mul_f32 v[114:115], v[114:115], v[166:167] op_sel_hi:[1,0]
	v_pk_fma_f32 v[112:113], v[188:189], v[112:113], v[204:205]
	v_pk_fma_f32 v[114:115], v[190:191], v[114:115], v[206:207]
	global_store_dwordx4 v133, v[112:115], s[88:89] offset:576
	s_waitcnt vmcnt(10)
; __device__ __forceinline__ void ln_phase(float* io, const float* __restrict__ g, const float* __restrict__ b, u16* outb) {
;     ...
;     float rstd = rsqrtf(q * (1.0f / DM) + LN_EPS);
; #pragma unroll
;     for (int i = 0; i < 8; ++i) {
;       int c = (i * 64 + lane) * 4;
;       float4 gg = *(const float4*)(g + c);
;       float4 bb = *(const float4*)(b + c);
;       float4 o;
;       o.x = v[i].x * rstd * gg.x + bb.x;
;       o.y = v[i].y * rstd * gg.y + bb.y;
;       o.z = v[i].z * rstd * gg.z + bb.z;
;       o.w = v[i].w * rstd * gg.w + bb.w;
;       *(float4*)(rp + c) = o;
;       if (outb) *(uint2*)((char*)outb + tl_off(row, c, DM >> 6)) = make_uint2(pack2(o.x, o.y), pack2(o.z, o.w));
	v_pk_mul_f32 v[152:153], v[152:153], s[16:17] op_sel_hi:[1,0]
	v_add_u32_e32 v133, 0x20000, v128
	v_fma_f32 v168, -v152, v152, v153
	v_max_f32_e32 v168, 0, v168
	v_add_f32_e32 v168, 0x3727c5ac, v168
	v_rsq_f32_e32 v168, v168
	s_nop 0
	v_pk_add_f32 v[108:109], v[108:109], v[152:153] op_sel_hi:[1,0] neg_lo:[0,1] neg_hi:[0,1]
	v_pk_add_f32 v[110:111], v[110:111], v[152:153] op_sel_hi:[1,0] neg_lo:[0,1] neg_hi:[0,1]
	v_pk_mul_f32 v[108:109], v[108:109], v[168:169] op_sel_hi:[1,0]
	v_pk_mul_f32 v[110:111], v[110:111], v[168:169] op_sel_hi:[1,0]
	v_pk_fma_f32 v[108:109], v[176:177], v[108:109], v[192:193]
	v_pk_fma_f32 v[110:111], v[178:179], v[110:111], v[194:195]
	global_store_dwordx4 v133, v[108:111], s[88:89]
	v_pk_add_f32 v[104:105], v[104:105], v[152:153] op_sel_hi:[1,0] neg_lo:[0,1] neg_hi:[0,1]
	v_pk_add_f32 v[106:107], v[106:107], v[152:153] op_sel_hi:[1,0] neg_lo:[0,1] neg_hi:[0,1]
	v_pk_mul_f32 v[104:105], v[104:105], v[168:169] op_sel_hi:[1,0]
	v_pk_mul_f32 v[106:107], v[106:107], v[168:169] op_sel_hi:[1,0]
	v_pk_fma_f32 v[104:105], v[180:181], v[104:105], v[196:197]
	v_pk_fma_f32 v[106:107], v[182:183], v[106:107], v[198:199]
	global_store_dwordx4 v133, v[104:107], s[88:89] offset:64
	v_pk_add_f32 v[100:101], v[100:101], v[152:153] op_sel_hi:[1,0] neg_lo:[0,1] neg_hi:[0,1]
	v_pk_add_f32 v[102:103], v[102:103], v[152:153] op_sel_hi:[1,0] neg_lo:[0,1] neg_hi:[0,1]
	v_pk_mul_f32 v[100:101], v[100:101], v[168:169] op_sel_hi:[1,0]
	v_pk_mul_f32 v[102:103], v[102:103], v[168:169] op_sel_hi:[1,0]
	v_pk_fma_f32 v[100:101], v[184:185], v[100:101], v[200:201]
	v_pk_fma_f32 v[102:103], v[186:187], v[102:103], v[202:203]
	global_store_dwordx4 v133, v[100:103], s[88:89] offset:512
	v_pk_add_f32 v[96:97], v[96:97], v[152:153] op_sel_hi:[1,0] neg_lo:[0,1] neg_hi:[0,1]
	v_pk_add_f32 v[98:99], v[98:99], v[152:153] op_sel_hi:[1,0] neg_lo:[0,1] neg_hi:[0,1]
	v_pk_mul_f32 v[96:97], v[96:97], v[168:169] op_sel_hi:[1,0]
	v_pk_mul_f32 v[98:99], v[98:99], v[168:169] op_sel_hi:[1,0]
	v_pk_fma_f32 v[96:97], v[188:189], v[96:97], v[204:205]
	v_pk_fma_f32 v[98:99], v[190:191], v[98:99], v[206:207]
	global_store_dwordx4 v133, v[96:99], s[88:89] offset:576
	s_waitcnt vmcnt(13)
	v_pk_mul_f32 v[154:155], v[154:155], s[16:17] op_sel_hi:[1,0]
	v_add_u32_e32 v133, 0x40000, v128
	v_fma_f32 v166, -v154, v154, v155
	v_max_f32_e32 v166, 0, v166
	v_add_f32_e32 v166, 0x3727c5ac, v166
	v_rsq_f32_e32 v166, v166
	s_nop 0
	v_pk_add_f32 v[92:93], v[92:93], v[154:155] op_sel_hi:[1,0] neg_lo:[0,1] neg_hi:[0,1]
	v_pk_add_f32 v[94:95], v[94:95], v[154:155] op_sel_hi:[1,0] neg_lo:[0,1] neg_hi:[0,1]
	v_pk_mul_f32 v[92:93], v[92:93], v[166:167] op_sel_hi:[1,0]
	v_pk_mul_f32 v[94:95], v[94:95], v[166:167] op_sel_hi:[1,0]
	v_pk_fma_f32 v[92:93], v[176:177], v[92:93], v[192:193]
	v_pk_fma_f32 v[94:95], v[178:179], v[94:95], v[194:195]
	global_store_dwordx4 v133, v[92:95], s[88:89]
	v_pk_add_f32 v[88:89], v[88:89], v[154:155] op_sel_hi:[1,0] neg_lo:[0,1] neg_hi:[0,1]
	v_pk_add_f32 v[90:91], v[90:91], v[154:155] op_sel_hi:[1,0] neg_lo:[0,1] neg_hi:[0,1]
	v_pk_mul_f32 v[88:89], v[88:89], v[166:167] op_sel_hi:[1,0]
	v_pk_mul_f32 v[90:91], v[90:91], v[166:167] op_sel_hi:[1,0]
	v_pk_fma_f32 v[88:89], v[180:181], v[88:89], v[196:197]
	v_pk_fma_f32 v[90:91], v[182:183], v[90:91], v[198:199]
	global_store_dwordx4 v133, v[88:91], s[88:89] offset:64
	v_pk_add_f32 v[84:85], v[84:85], v[154:155] op_sel_hi:[1,0] neg_lo:[0,1] neg_hi:[0,1]
	v_pk_add_f32 v[86:87], v[86:87], v[154:155] op_sel_hi:[1,0] neg_lo:[0,1] neg_hi:[0,1]
	v_pk_mul_f32 v[84:85], v[84:85], v[166:167] op_sel_hi:[1,0]
	v_pk_mul_f32 v[86:87], v[86:87], v[166:167] op_sel_hi:[1,0]
	v_pk_fma_f32 v[84:85], v[184:185], v[84:85], v[200:201]
	v_pk_fma_f32 v[86:87], v[186:187], v[86:87], v[202:203]
	global_store_dwordx4 v133, v[84:87], s[88:89] offset:512
	v_pk_add_f32 v[80:81], v[80:81], v[154:155] op_sel_hi:[1,0] neg_lo:[0,1] neg_hi:[0,1]
	v_pk_add_f32 v[82:83], v[82:83], v[154:155] op_sel_hi:[1,0] neg_lo:[0,1] neg_hi:[0,1]
	v_pk_mul_f32 v[80:81], v[80:81], v[166:167] op_sel_hi:[1,0]
	v_pk_mul_f32 v[82:83], v[82:83], v[166:167] op_sel_hi:[1,0]
	v_pk_fma_f32 v[80:81], v[188:189], v[80:81], v[204:205]
	v_pk_fma_f32 v[82:83], v[190:191], v[82:83], v[206:207]
	global_store_dwordx4 v133, v[80:83], s[88:89] offset:576
	s_waitcnt vmcnt(16)
	v_pk_mul_f32 v[156:157], v[156:157], s[16:17] op_sel_hi:[1,0]
	v_add_u32_e32 v133, 0x60000, v128
	v_fma_f32 v168, -v156, v156, v157
	v_max_f32_e32 v168, 0, v168
	v_add_f32_e32 v168, 0x3727c5ac, v168
	v_rsq_f32_e32 v168, v168
	s_nop 0
	v_pk_add_f32 v[76:77], v[76:77], v[156:157] op_sel_hi:[1,0] neg_lo:[0,1] neg_hi:[0,1]
	v_pk_add_f32 v[78:79], v[78:79], v[156:157] op_sel_hi:[1,0] neg_lo:[0,1] neg_hi:[0,1]
	v_pk_mul_f32 v[76:77], v[76:77], v[168:169] op_sel_hi:[1,0]
	v_pk_mul_f32 v[78:79], v[78:79], v[168:169] op_sel_hi:[1,0]
	v_pk_fma_f32 v[76:77], v[176:177], v[76:77], v[192:193]
	v_pk_fma_f32 v[78:79], v[178:179], v[78:79], v[194:195]
	global_store_dwordx4 v133, v[76:79], s[88:89]
	v_pk_add_f32 v[72:73], v[72:73], v[156:157] op_sel_hi:[1,0] neg_lo:[0,1] neg_hi:[0,1]
	v_pk_add_f32 v[74:75], v[74:75], v[156:157] op_sel_hi:[1,0] neg_lo:[0,1] neg_hi:[0,1]
	v_pk_mul_f32 v[72:73], v[72:73], v[168:169] op_sel_hi:[1,0]
	v_pk_mul_f32 v[74:75], v[74:75], v[168:169] op_sel_hi:[1,0]
	v_pk_fma_f32 v[72:73], v[180:181], v[72:73], v[196:197]
	v_pk_fma_f32 v[74:75], v[182:183], v[74:75], v[198:199]
	global_store_dwordx4 v133, v[72:75], s[88:89] offset:64
	v_pk_add_f32 v[68:69], v[68:69], v[156:157] op_sel_hi:[1,0] neg_lo:[0,1] neg_hi:[0,1]
	v_pk_add_f32 v[70:71], v[70:71], v[156:157] op_sel_hi:[1,0] neg_lo:[0,1] neg_hi:[0,1]
	v_pk_mul_f32 v[68:69], v[68:69], v[168:169] op_sel_hi:[1,0]
	v_pk_mul_f32 v[70:71], v[70:71], v[168:169] op_sel_hi:[1,0]
	v_pk_fma_f32 v[68:69], v[184:185], v[68:69], v[200:201]
	v_pk_fma_f32 v[70:71], v[186:187], v[70:71], v[202:203]
	global_store_dwordx4 v133, v[68:71], s[88:89] offset:512
	v_pk_add_f32 v[64:65], v[64:65], v[156:157] op_sel_hi:[1,0] neg_lo:[0,1] neg_hi:[0,1]
	v_pk_add_f32 v[66:67], v[66:67], v[156:157] op_sel_hi:[1,0] neg_lo:[0,1] neg_hi:[0,1]
	v_pk_mul_f32 v[64:65], v[64:65], v[168:169] op_sel_hi:[1,0]
	v_pk_mul_f32 v[66:67], v[66:67], v[168:169] op_sel_hi:[1,0]
	v_pk_fma_f32 v[64:65], v[188:189], v[64:65], v[204:205]
	v_pk_fma_f32 v[66:67], v[190:191], v[66:67], v[206:207]
	global_store_dwordx4 v133, v[64:67], s[88:89] offset:576
	s_waitcnt vmcnt(19)
; __device__ __forceinline__ void ln_phase(float* io, const float* __restrict__ g, const float* __restrict__ b, u16* outb) {
;     ...
;     float rstd = rsqrtf(q * (1.0f / DM) + LN_EPS);
; #pragma unroll
;     for (int i = 0; i < 8; ++i) {
;       int c = (i * 64 + lane) * 4;
;       float4 gg = *(const float4*)(g + c);
;       float4 bb = *(const float4*)(b + c);
;       float4 o;
;       o.x = v[i].x * rstd * gg.x + bb.x;
;       o.y = v[i].y * rstd * gg.y + bb.y;
;       o.z = v[i].z * rstd * gg.z + bb.z;
;       o.w = v[i].w * rstd * gg.w + bb.w;
;       *(float4*)(rp + c) = o;
; __device__ __forceinline__ void row_stats(const float* st, int row, float& mu, float& rstd) {
;   float2 v = *(const float2*)(st + (size_t)row * 2);
;   mu = v.x * (1.0f / DM);
;   float var = fmaxf(v.y * (1.0f / DM) - mu * mu, 0.f);
;   rstd = rsqrtf(var + LN_EPS);
; }
	v_pk_mul_f32 v[158:159], v[158:159], s[16:17] op_sel_hi:[1,0]
	v_add_u32_e32 v133, 0x100000, v128
	v_fma_f32 v166, -v158, v158, v159
	v_max_f32_e32 v166, 0, v166
	v_add_f32_e32 v166, 0x3727c5ac, v166
	v_rsq_f32_e32 v166, v166
	s_nop 0
	v_pk_add_f32 v[60:61], v[60:61], v[158:159] op_sel_hi:[1,0] neg_lo:[0,1] neg_hi:[0,1]
	v_pk_add_f32 v[62:63], v[62:63], v[158:159] op_sel_hi:[1,0] neg_lo:[0,1] neg_hi:[0,1]
	v_pk_mul_f32 v[60:61], v[60:61], v[166:167] op_sel_hi:[1,0]
	v_pk_mul_f32 v[62:63], v[62:63], v[166:167] op_sel_hi:[1,0]
	v_pk_fma_f32 v[60:61], v[176:177], v[60:61], v[192:193]
	v_pk_fma_f32 v[62:63], v[178:179], v[62:63], v[194:195]
	global_store_dwordx4 v133, v[60:63], s[88:89]
	v_pk_add_f32 v[56:57], v[56:57], v[158:159] op_sel_hi:[1,0] neg_lo:[0,1] neg_hi:[0,1]
	v_pk_add_f32 v[58:59], v[58:59], v[158:159] op_sel_hi:[1,0] neg_lo:[0,1] neg_hi:[0,1]
	v_pk_mul_f32 v[56:57], v[56:57], v[166:167] op_sel_hi:[1,0]
	v_pk_mul_f32 v[58:59], v[58:59], v[166:167] op_sel_hi:[1,0]
	v_pk_fma_f32 v[56:57], v[180:181], v[56:57], v[196:197]
	v_pk_fma_f32 v[58:59], v[182:183], v[58:59], v[198:199]
	global_store_dwordx4 v133, v[56:59], s[88:89] offset:64
	v_pk_add_f32 v[52:53], v[52:53], v[158:159] op_sel_hi:[1,0] neg_lo:[0,1] neg_hi:[0,1]
	v_pk_add_f32 v[54:55], v[54:55], v[158:159] op_sel_hi:[1,0] neg_lo:[0,1] neg_hi:[0,1]
	v_pk_mul_f32 v[52:53], v[52:53], v[166:167] op_sel_hi:[1,0]
	v_pk_mul_f32 v[54:55], v[54:55], v[166:167] op_sel_hi:[1,0]
	v_pk_fma_f32 v[52:53], v[184:185], v[52:53], v[200:201]
	v_pk_fma_f32 v[54:55], v[186:187], v[54:55], v[202:203]
	global_store_dwordx4 v133, v[52:55], s[88:89] offset:512
	v_pk_add_f32 v[48:49], v[48:49], v[158:159] op_sel_hi:[1,0] neg_lo:[0,1] neg_hi:[0,1]
	v_pk_add_f32 v[50:51], v[50:51], v[158:159] op_sel_hi:[1,0] neg_lo:[0,1] neg_hi:[0,1]
	v_pk_mul_f32 v[48:49], v[48:49], v[166:167] op_sel_hi:[1,0]
	v_pk_mul_f32 v[50:51], v[50:51], v[166:167] op_sel_hi:[1,0]
	v_pk_fma_f32 v[48:49], v[188:189], v[48:49], v[204:205]
	v_pk_fma_f32 v[50:51], v[190:191], v[50:51], v[206:207]
	global_store_dwordx4 v133, v[48:51], s[88:89] offset:576
	s_waitcnt vmcnt(22)
	v_pk_mul_f32 v[160:161], v[160:161], s[16:17] op_sel_hi:[1,0]
	v_add_u32_e32 v133, 0x120000, v128
	v_fma_f32 v168, -v160, v160, v161
	v_max_f32_e32 v168, 0, v168
	v_add_f32_e32 v168, 0x3727c5ac, v168
	v_rsq_f32_e32 v168, v168
	s_nop 0
	v_pk_add_f32 v[44:45], v[44:45], v[160:161] op_sel_hi:[1,0] neg_lo:[0,1] neg_hi:[0,1]
	v_pk_add_f32 v[46:47], v[46:47], v[160:161] op_sel_hi:[1,0] neg_lo:[0,1] neg_hi:[0,1]
	v_pk_mul_f32 v[44:45], v[44:45], v[168:169] op_sel_hi:[1,0]
	v_pk_mul_f32 v[46:47], v[46:47], v[168:169] op_sel_hi:[1,0]
	v_pk_fma_f32 v[44:45], v[176:177], v[44:45], v[192:193]
	v_pk_fma_f32 v[46:47], v[178:179], v[46:47], v[194:195]
	global_store_dwordx4 v133, v[44:47], s[88:89]
	v_pk_add_f32 v[40:41], v[40:41], v[160:161] op_sel_hi:[1,0] neg_lo:[0,1] neg_hi:[0,1]
	v_pk_add_f32 v[42:43], v[42:43], v[160:161] op_sel_hi:[1,0] neg_lo:[0,1] neg_hi:[0,1]
	v_pk_mul_f32 v[40:41], v[40:41], v[168:169] op_sel_hi:[1,0]
	v_pk_mul_f32 v[42:43], v[42:43], v[168:169] op_sel_hi:[1,0]
	v_pk_fma_f32 v[40:41], v[180:181], v[40:41], v[196:197]
	v_pk_fma_f32 v[42:43], v[182:183], v[42:43], v[198:199]
	global_store_dwordx4 v133, v[40:43], s[88:89] offset:64
	v_pk_add_f32 v[36:37], v[36:37], v[160:161] op_sel_hi:[1,0] neg_lo:[0,1] neg_hi:[0,1]
	v_pk_add_f32 v[38:39], v[38:39], v[160:161] op_sel_hi:[1,0] neg_lo:[0,1] neg_hi:[0,1]
	v_pk_mul_f32 v[36:37], v[36:37], v[168:169] op_sel_hi:[1,0]
	v_pk_mul_f32 v[38:39], v[38:39], v[168:169] op_sel_hi:[1,0]
	v_pk_fma_f32 v[36:37], v[184:185], v[36:37], v[200:201]
	v_pk_fma_f32 v[38:39], v[186:187], v[38:39], v[202:203]
	global_store_dwordx4 v133, v[36:39], s[88:89] offset:512
	v_pk_add_f32 v[32:33], v[32:33], v[160:161] op_sel_hi:[1,0] neg_lo:[0,1] neg_hi:[0,1]
	v_pk_add_f32 v[34:35], v[34:35], v[160:161] op_sel_hi:[1,0] neg_lo:[0,1] neg_hi:[0,1]
	v_pk_mul_f32 v[32:33], v[32:33], v[168:169] op_sel_hi:[1,0]
	v_pk_mul_f32 v[34:35], v[34:35], v[168:169] op_sel_hi:[1,0]
	v_pk_fma_f32 v[32:33], v[188:189], v[32:33], v[204:205]
	v_pk_fma_f32 v[34:35], v[190:191], v[34:35], v[206:207]
	global_store_dwordx4 v133, v[32:35], s[88:89] offset:576
	s_waitcnt vmcnt(25)
; __device__ __forceinline__ void ln_phase(float* io, const float* __restrict__ g, const float* __restrict__ b, u16* outb) {
;     ...
;     float rstd = rsqrtf(q * (1.0f / DM) + LN_EPS);
; #pragma unroll
;     for (int i = 0; i < 8; ++i) {
;       int c = (i * 64 + lane) * 4;
;       float4 gg = *(const float4*)(g + c);
;       float4 bb = *(const float4*)(b + c);
;       float4 o;
;       o.x = v[i].x * rstd * gg.x + bb.x;
;       o.y = v[i].y * rstd * gg.y + bb.y;
;       o.z = v[i].z * rstd * gg.z + bb.z;
;       o.w = v[i].w * rstd * gg.w + bb.w;
;       *(float4*)(rp + c) = o;
; __device__ __forceinline__ void row_stats(const float* st, int row, float& mu, float& rstd) {
;   float2 v = *(const float2*)(st + (size_t)row * 2);
;   mu = v.x * (1.0f / DM);
;   float var = fmaxf(v.y * (1.0f / DM) - mu * mu, 0.f);
;   rstd = rsqrtf(var + LN_EPS);
; }
	v_pk_mul_f32 v[162:163], v[162:163], s[16:17] op_sel_hi:[1,0]
	v_add_u32_e32 v133, 0x140000, v128
	v_fma_f32 v166, -v162, v162, v163
	v_max_f32_e32 v166, 0, v166
	v_add_f32_e32 v166, 0x3727c5ac, v166
	v_rsq_f32_e32 v166, v166
	s_nop 0
	v_pk_add_f32 v[28:29], v[28:29], v[162:163] op_sel_hi:[1,0] neg_lo:[0,1] neg_hi:[0,1]
	v_pk_add_f32 v[30:31], v[30:31], v[162:163] op_sel_hi:[1,0] neg_lo:[0,1] neg_hi:[0,1]
	v_pk_mul_f32 v[28:29], v[28:29], v[166:167] op_sel_hi:[1,0]
	v_pk_mul_f32 v[30:31], v[30:31], v[166:167] op_sel_hi:[1,0]
	v_pk_fma_f32 v[28:29], v[176:177], v[28:29], v[192:193]
	v_pk_fma_f32 v[30:31], v[178:179], v[30:31], v[194:195]
	global_store_dwordx4 v133, v[28:31], s[88:89]
	v_pk_add_f32 v[24:25], v[24:25], v[162:163] op_sel_hi:[1,0] neg_lo:[0,1] neg_hi:[0,1]
	v_pk_add_f32 v[26:27], v[26:27], v[162:163] op_sel_hi:[1,0] neg_lo:[0,1] neg_hi:[0,1]
	v_pk_mul_f32 v[24:25], v[24:25], v[166:167] op_sel_hi:[1,0]
	v_pk_mul_f32 v[26:27], v[26:27], v[166:167] op_sel_hi:[1,0]
	v_pk_fma_f32 v[24:25], v[180:181], v[24:25], v[196:197]
	v_pk_fma_f32 v[26:27], v[182:183], v[26:27], v[198:199]
	global_store_dwordx4 v133, v[24:27], s[88:89] offset:64
	v_pk_add_f32 v[20:21], v[20:21], v[162:163] op_sel_hi:[1,0] neg_lo:[0,1] neg_hi:[0,1]
	v_pk_add_f32 v[22:23], v[22:23], v[162:163] op_sel_hi:[1,0] neg_lo:[0,1] neg_hi:[0,1]
	v_pk_mul_f32 v[20:21], v[20:21], v[166:167] op_sel_hi:[1,0]
	v_pk_mul_f32 v[22:23], v[22:23], v[166:167] op_sel_hi:[1,0]
	v_pk_fma_f32 v[20:21], v[184:185], v[20:21], v[200:201]
	v_pk_fma_f32 v[22:23], v[186:187], v[22:23], v[202:203]
	global_store_dwordx4 v133, v[20:23], s[88:89] offset:512
	v_pk_add_f32 v[16:17], v[16:17], v[162:163] op_sel_hi:[1,0] neg_lo:[0,1] neg_hi:[0,1]
	v_pk_add_f32 v[18:19], v[18:19], v[162:163] op_sel_hi:[1,0] neg_lo:[0,1] neg_hi:[0,1]
	v_pk_mul_f32 v[16:17], v[16:17], v[166:167] op_sel_hi:[1,0]
	v_pk_mul_f32 v[18:19], v[18:19], v[166:167] op_sel_hi:[1,0]
	v_pk_fma_f32 v[16:17], v[188:189], v[16:17], v[204:205]
	v_pk_fma_f32 v[18:19], v[190:191], v[18:19], v[206:207]
	global_store_dwordx4 v133, v[16:19], s[88:89] offset:576
	s_waitcnt vmcnt(28)
	v_pk_mul_f32 v[164:165], v[164:165], s[16:17] op_sel_hi:[1,0]
	v_add_u32_e32 v133, 0x160000, v128
	v_fma_f32 v168, -v164, v164, v165
	v_max_f32_e32 v168, 0, v168
	v_add_f32_e32 v168, 0x3727c5ac, v168
	v_rsq_f32_e32 v168, v168
	s_nop 0
	v_pk_add_f32 v[12:13], v[12:13], v[164:165] op_sel_hi:[1,0] neg_lo:[0,1] neg_hi:[0,1]
	v_pk_add_f32 v[14:15], v[14:15], v[164:165] op_sel_hi:[1,0] neg_lo:[0,1] neg_hi:[0,1]
	v_pk_mul_f32 v[12:13], v[12:13], v[168:169] op_sel_hi:[1,0]
	v_pk_mul_f32 v[14:15], v[14:15], v[168:169] op_sel_hi:[1,0]
	v_pk_fma_f32 v[12:13], v[176:177], v[12:13], v[192:193]
	v_pk_fma_f32 v[14:15], v[178:179], v[14:15], v[194:195]
	global_store_dwordx4 v133, v[12:15], s[88:89]
	v_pk_add_f32 v[8:9], v[8:9], v[164:165] op_sel_hi:[1,0] neg_lo:[0,1] neg_hi:[0,1]
	v_pk_add_f32 v[10:11], v[10:11], v[164:165] op_sel_hi:[1,0] neg_lo:[0,1] neg_hi:[0,1]
	v_pk_mul_f32 v[8:9], v[8:9], v[168:169] op_sel_hi:[1,0]
	v_pk_mul_f32 v[10:11], v[10:11], v[168:169] op_sel_hi:[1,0]
	v_pk_fma_f32 v[8:9], v[180:181], v[8:9], v[196:197]
	v_pk_fma_f32 v[10:11], v[182:183], v[10:11], v[198:199]
	global_store_dwordx4 v133, v[8:11], s[88:89] offset:64
	v_pk_add_f32 v[4:5], v[4:5], v[164:165] op_sel_hi:[1,0] neg_lo:[0,1] neg_hi:[0,1]
	v_pk_add_f32 v[6:7], v[6:7], v[164:165] op_sel_hi:[1,0] neg_lo:[0,1] neg_hi:[0,1]
	v_pk_mul_f32 v[4:5], v[4:5], v[168:169] op_sel_hi:[1,0]
	v_pk_mul_f32 v[6:7], v[6:7], v[168:169] op_sel_hi:[1,0]
	v_pk_fma_f32 v[4:5], v[184:185], v[4:5], v[200:201]
	v_pk_fma_f32 v[6:7], v[186:187], v[6:7], v[202:203]
	global_store_dwordx4 v133, v[4:7], s[88:89] offset:512
	v_pk_add_f32 v[0:1], v[0:1], v[164:165] op_sel_hi:[1,0] neg_lo:[0,1] neg_hi:[0,1]
	v_pk_add_f32 v[2:3], v[2:3], v[164:165] op_sel_hi:[1,0] neg_lo:[0,1] neg_hi:[0,1]
	v_pk_mul_f32 v[0:1], v[0:1], v[168:169] op_sel_hi:[1,0]
	v_pk_mul_f32 v[2:3], v[2:3], v[168:169] op_sel_hi:[1,0]
	v_pk_fma_f32 v[0:1], v[188:189], v[0:1], v[204:205]
	v_pk_fma_f32 v[2:3], v[190:191], v[2:3], v[206:207]
	global_store_dwordx4 v133, v[0:3], s[88:89] offset:576
	s_mov_b32 s33, s46
	s_mov_b32 s47, s45
	s_andn2_b64 vcc, exec, s[20:21]
	s_cbranch_vccz .LBB0_636

; __device__ __forceinline__ unsigned xb_add(unsigned* p, unsigned v) { return __hip_atomic_fetch_add(p, v, __ATOMIC_RELAXED, __HIP_MEMORY_SCOPE_AGENT); }
; __device__ __forceinline__ void xcd_barrier(const XcdBarrier& b) {
;     asm volatile("s_waitcnt vmcnt(0)" ::: "memory");
;     __syncthreads();
;     if (threadIdx.x == 0) {
;         unsigned* bar = b.bar;
;         __builtin_amdgcn_s_waitcnt(0);
;         const unsigned old = xb_add(&bar[XB_XSUB(b.x)], 1u);
;         const unsigned gen = old / b.nloc;
;         if (old + 1u == (gen + 1u) * b.nloc) {
.LBB0_637:
	s_branch .LBB0_680
	s_cmp_gt_i32 s92, 8
	s_cselect_b64 s[2:3], -1, 0
	s_cmp_lt_i32 s93, 9
	s_cselect_b64 s[4:5], -1, 0
	s_or_b64 s[2:3], s[2:3], s[4:5]
	s_and_b64 vcc, exec, s[2:3]
	s_cbranch_vccnz .LBB0_680
	s_xor_b64 s[0:1], s[0:1], -1
	s_andn2_b64 vcc, exec, s[0:1]
	s_cbranch_vccnz .LBB0_677
	s_waitcnt vmcnt(0)
	s_waitcnt vmcnt(0)
	s_barrier
	s_mov_b64 s[0:1], exec
	v_readlane_b32 s2, v244, 4
	v_readlane_b32 s3, v244, 5
	s_and_b64 s[2:3], s[0:1], s[2:3]
	s_mov_b64 exec, s[2:3]
	s_cbranch_execz .LBB0_676
	s_mov_b64 s[2:3], exec
	v_mbcnt_lo_u32_b32 v0, s2, 0
	v_readlane_b32 s4, v244, 6
	v_mbcnt_hi_u32_b32 v0, s3, v0
	s_lshl_b32 s20, s4, 6
	s_mov_b32 s7, 0
	v_cmp_eq_u32_e32 vcc, 0, v0
	s_waitcnt vmcnt(0) expcnt(0) lgkmcnt(0)
	s_and_saveexec_b64 s[4:5], vcc
	s_cbranch_execz .LBB0_642
	s_add_i32 s6, s20, 0x500
	s_lshl_b64 s[6:7], s[6:7], 2
	v_readlane_b32 s8, v244, 2
	v_readlane_b32 s9, v244, 3
	s_add_u32 s6, s8, s6
	s_addc_u32 s7, s9, s7
	s_bcnt1_i32_b64 s2, s[2:3]
	v_mov_b32_e32 v1, 0
	v_mov_b32_e32 v2, s2
	global_atomic_add v1, v1, v2, s[6:7] sc0
